# adds: P1 bf16-store epilogue path specialised per category (uniform branches folded, straight-line)
# speedup vs baseline: 1.0073x; 1.0073x over previous
; __device__ __forceinline__ float fsilu(float x) { return x * __builtin_amdgcn_rcpf(1.f + __expf(-x)); }
;     __device__ __forceinline__ void operator()(const f32x4 (&acc)[2][2][4][2], const pg8::Unit& u, int wr, int wc, int fr, int fq) const {
;     ...
;         if (cat == 0 || cat == 3 || cat == 4 || cat == 6 || cat == 7) {
;             bf16_t* base; int pitch;
;             if (cat == 0) { base = (bf16_t*)(ws + WS_QB); pitch = 512; } else if (cat == 3) { base = (bf16_t*)(ws + WS_YC); pitch = 1024; }
;             else if (cat == 4) { base = (bf16_t*)(ws + WS_QE); pitch = 512; } else if (cat == 6) { base = (bf16_t*)(ws + WS_VTH); pitch = 512; } else { base = (bf16_t*)(ws + WS_YC) + 512; pitch = 1024; }
; #pragma unroll
;             for (int ai = 0; ai < 2; ++ai)
; #pragma unroll
;                 for (int m = 0; m < 4; ++m) { const int r = rowb + ai * 128 + m * 16; const float sc = rs[ai][m];
; #pragma unroll
;                     for (int bj = 0; bj < 2; ++bj) { u32x4 w;
; #pragma unroll
;                         for (int n = 0; n < 2; ++n) { f32x4 v = acc[ai][bj][m][n] * sc;
;                             if (cat == 0) v = v * QSCALE; else if (cat != 6) { v[0] = fsilu(v[0]); v[1] = fsilu(v[1]); v[2] = fsilu(v[2]); v[3] = fsilu(v[3]); }
;                             w[2 * n] = pk2(v[0], v[1]); w[2 * n + 1] = pk2(v[2], v[3]); }
;                         *(u32x4*)(base + (size_t)r * pitch + cb + bj * 128) = w; } }
.LBB0_233:
	s_and_b64 vcc, exec, s[42:43]
	s_cbranch_vccnz .Lbf16_q
	s_cmp_eq_u32 s47, 6
	s_cbranch_scc1 .Lbf16_plain
	s_cmp_lg_u32 s47, 6
	s_cselect_b64 s[6:7], -1, 0
	s_waitcnt lgkmcnt(0)
	v_pk_mul_f32 v[162:163], v[158:159], v[200:201] op_sel_hi:[1,0]
	v_cndmask_b32_e64 v158, 0, 1, s[6:7]
	v_pk_mul_f32 v[164:165], v[160:161], v[200:201] op_sel_hi:[1,0]
	v_cmp_ne_u32_e64 s[44:45], 1, v158
	s_movk_i32 s57, 0x4000
	v_mov_b64_e32 v[158:159], v[162:163]
	v_mov_b64_e32 v[160:161], v[164:165]
	v_mul_f32_e32 v158, 0xbfb8aa3b, v162
	v_mul_f32_e32 v159, 0xbfb8aa3b, v163
	v_mul_f32_e32 v160, 0xbfb8aa3b, v164
	v_mul_f32_e32 v161, 0xbfb8aa3b, v165
	v_exp_f32_e32 v158, v158
	v_exp_f32_e32 v159, v159
	v_exp_f32_e32 v160, v160
	v_exp_f32_e32 v161, v161
	v_add_f32_e32 v158, 1.0, v158
	v_add_f32_e32 v159, 1.0, v159
	v_add_f32_e32 v160, 1.0, v160
	v_add_f32_e32 v161, 1.0, v161
	v_rcp_f32_e32 v158, v158
	v_rcp_f32_e32 v160, v160
	v_rcp_f32_e32 v161, v161
	v_rcp_f32_e32 v159, v159
	v_pk_mul_f32 v[160:161], v[164:165], v[160:161]
	v_pk_mul_f32 v[158:159], v[162:163], v[158:159]
	v_mov_b32_e32 v166, v200
	v_mov_b32_e32 v167, v200
	v_mov_b32_e32 v162, v200
	v_mov_b32_e32 v163, v200
	v_pk_mul_f32 v[156:157], v[156:157], v[162:163]
	v_pk_mul_f32 v[154:155], v[154:155], v[166:167]
	v_mov_b64_e32 v[164:165], v[156:157]
	v_mov_b64_e32 v[162:163], v[154:155]
	v_mul_f32_e32 v162, 0xbfb8aa3b, v154
	v_mul_f32_e32 v163, 0xbfb8aa3b, v155
	v_mul_f32_e32 v164, 0xbfb8aa3b, v156
	v_mul_f32_e32 v165, 0xbfb8aa3b, v157
	v_exp_f32_e32 v162, v162
	v_exp_f32_e32 v163, v163
	v_exp_f32_e32 v164, v164
	v_exp_f32_e32 v165, v165
	v_add_f32_e32 v162, 1.0, v162
	v_add_f32_e32 v163, 1.0, v163
	v_add_f32_e32 v164, 1.0, v164
	v_add_f32_e32 v165, 1.0, v165
	v_rcp_f32_e32 v162, v162
	v_rcp_f32_e32 v164, v164
	v_rcp_f32_e32 v165, v165
	v_rcp_f32_e32 v163, v163
	v_pk_mul_f32 v[164:165], v[156:157], v[164:165]
	v_pk_mul_f32 v[162:163], v[154:155], v[162:163]
	s_add_u32 s6, s22, s60
	s_addc_u32 s7, s23, s61
	v_ashrrev_i32_e32 v203, 31, v202
	v_cvt_pk_bf16_f32 v154, v158, v159
	v_lshl_add_u64 v[158:159], v[202:203], 1, s[6:7]
	v_mad_i64_i32 v[156:157], s[6:7], s56, v192, 0
	v_cvt_pk_bf16_f32 v155, v160, v161
	v_lshl_add_u64 v[160:161], v[156:157], 1, v[158:159]
	v_cvt_pk_bf16_f32 v156, v162, v163
	v_cvt_pk_bf16_f32 v157, v164, v165
	global_store_dwordx4 v[160:161], v[154:157], off
	s_nop 1
	v_mov_b32_e32 v154, v200
	v_mov_b32_e32 v155, v200
	v_pk_mul_f32 v[156:157], v[152:153], v[154:155]
	v_pk_mul_f32 v[154:155], v[150:151], v[166:167]
	v_mov_b64_e32 v[150:151], v[154:155]
	v_mov_b64_e32 v[152:153], v[156:157]
	v_mul_f32_e32 v150, 0xbfb8aa3b, v154
	v_mul_f32_e32 v151, 0xbfb8aa3b, v155
	v_mul_f32_e32 v152, 0xbfb8aa3b, v156
	v_mul_f32_e32 v153, 0xbfb8aa3b, v157
	v_exp_f32_e32 v150, v150
	v_exp_f32_e32 v151, v151
	v_exp_f32_e32 v152, v152
	v_exp_f32_e32 v153, v153
	v_add_f32_e32 v150, 1.0, v150
	v_add_f32_e32 v151, 1.0, v151
	v_add_f32_e32 v152, 1.0, v152
	v_add_f32_e32 v153, 1.0, v153
	v_rcp_f32_e32 v150, v150
	v_rcp_f32_e32 v152, v152
	v_rcp_f32_e32 v153, v153
	v_rcp_f32_e32 v151, v151
	v_pk_mul_f32 v[152:153], v[156:157], v[152:153]
	v_pk_mul_f32 v[150:151], v[154:155], v[150:151]
	v_mov_b32_e32 v154, v200
	v_mov_b32_e32 v155, v200
	v_pk_mul_f32 v[148:149], v[148:149], v[154:155]
	v_pk_mul_f32 v[146:147], v[146:147], v[166:167]
	v_mov_b64_e32 v[156:157], v[148:149]
	v_mov_b64_e32 v[154:155], v[146:147]
	v_mul_f32_e32 v154, 0xbfb8aa3b, v146
	v_mul_f32_e32 v155, 0xbfb8aa3b, v147
	v_mul_f32_e32 v156, 0xbfb8aa3b, v148
	v_mul_f32_e32 v157, 0xbfb8aa3b, v149
	v_exp_f32_e32 v154, v154
	v_exp_f32_e32 v155, v155
	v_exp_f32_e32 v156, v156
	v_exp_f32_e32 v157, v157
	v_add_f32_e32 v154, 1.0, v154
	v_add_f32_e32 v155, 1.0, v155
	v_add_f32_e32 v156, 1.0, v156
	v_add_f32_e32 v157, 1.0, v157
	v_rcp_f32_e32 v154, v154
	v_rcp_f32_e32 v156, v156
	v_rcp_f32_e32 v157, v157
	v_rcp_f32_e32 v155, v155
	v_pk_mul_f32 v[156:157], v[148:149], v[156:157]
	v_pk_mul_f32 v[154:155], v[146:147], v[154:155]
	v_cvt_pk_bf16_f32 v146, v150, v151
	v_cvt_pk_bf16_f32 v147, v152, v153
	v_cvt_pk_bf16_f32 v148, v154, v155
	v_cvt_pk_bf16_f32 v149, v156, v157
	global_store_dwordx4 v[160:161], v[146:149], off offset:256
	s_nop 1
	v_pk_mul_f32 v[146:147], v[142:143], v[200:201] op_sel:[0,1]
	v_pk_mul_f32 v[148:149], v[144:145], v[200:201] op_sel:[0,1]
	v_mov_b64_e32 v[142:143], v[146:147]
	v_mov_b64_e32 v[144:145], v[148:149]
	v_mul_f32_e32 v142, 0xbfb8aa3b, v146
	v_mul_f32_e32 v143, 0xbfb8aa3b, v147
	v_mul_f32_e32 v144, 0xbfb8aa3b, v148
	v_mul_f32_e32 v145, 0xbfb8aa3b, v149
	v_exp_f32_e32 v142, v142
	v_exp_f32_e32 v143, v143
	v_exp_f32_e32 v144, v144
	v_exp_f32_e32 v145, v145
	v_add_f32_e32 v142, 1.0, v142
	v_add_f32_e32 v143, 1.0, v143
	v_add_f32_e32 v144, 1.0, v144
	v_add_f32_e32 v145, 1.0, v145
	v_rcp_f32_e32 v142, v142
	v_rcp_f32_e32 v144, v144
	v_rcp_f32_e32 v145, v145
	v_rcp_f32_e32 v143, v143
	v_pk_mul_f32 v[144:145], v[148:149], v[144:145]
	v_pk_mul_f32 v[142:143], v[146:147], v[142:143]
	v_mov_b32_e32 v200, v201
	v_mov_b32_e32 v146, v201
	v_mov_b32_e32 v147, v201
	v_pk_mul_f32 v[140:141], v[140:141], v[146:147]
	v_pk_mul_f32 v[138:139], v[138:139], v[200:201]
	v_mov_b64_e32 v[148:149], v[140:141]
	v_mov_b64_e32 v[146:147], v[138:139]
	v_mul_f32_e32 v146, 0xbfb8aa3b, v138
	v_mul_f32_e32 v147, 0xbfb8aa3b, v139
	v_mul_f32_e32 v148, 0xbfb8aa3b, v140
	v_mul_f32_e32 v149, 0xbfb8aa3b, v141
	v_exp_f32_e32 v146, v146
	v_exp_f32_e32 v147, v147
	v_exp_f32_e32 v148, v148
	v_exp_f32_e32 v149, v149
	v_add_f32_e32 v146, 1.0, v146
	v_add_f32_e32 v147, 1.0, v147
	v_add_f32_e32 v148, 1.0, v148
	v_add_f32_e32 v149, 1.0, v149
	v_rcp_f32_e32 v146, v146
; __device__ __forceinline__ float fsilu(float x) { return x * __builtin_amdgcn_rcpf(1.f + __expf(-x)); }
;     __device__ __forceinline__ void operator()(const f32x4 (&acc)[2][2][4][2], const pg8::Unit& u, int wr, int wc, int fr, int fq) const {
;     ...
;                 for (int m = 0; m < 4; ++m) { const int r = rowb + ai * 128 + m * 16; const float sc = rs[ai][m];
; #pragma unroll
;                     for (int bj = 0; bj < 2; ++bj) { u32x4 w;
; #pragma unroll
;                         for (int n = 0; n < 2; ++n) { f32x4 v = acc[ai][bj][m][n] * sc;
;                             if (cat == 0) v = v * QSCALE; else if (cat != 6) { v[0] = fsilu(v[0]); v[1] = fsilu(v[1]); v[2] = fsilu(v[2]); v[3] = fsilu(v[3]); }
;                             w[2 * n] = pk2(v[0], v[1]); w[2 * n + 1] = pk2(v[2], v[3]); }
;                         *(u32x4*)(base + (size_t)r * pitch + cb + bj * 128) = w; } }
	v_rcp_f32_e32 v148, v148
	v_rcp_f32_e32 v149, v149
	v_rcp_f32_e32 v147, v147
	v_pk_mul_f32 v[148:149], v[140:141], v[148:149]
	v_pk_mul_f32 v[146:147], v[138:139], v[146:147]
	v_add_u32_e32 v140, 16, v192
	v_mad_i64_i32 v[140:141], s[6:7], s56, v140, 0
	v_cvt_pk_bf16_f32 v138, v142, v143
	v_cvt_pk_bf16_f32 v139, v144, v145
	v_lshl_add_u64 v[142:143], v[140:141], 1, v[158:159]
	v_cvt_pk_bf16_f32 v140, v146, v147
	v_cvt_pk_bf16_f32 v141, v148, v149
	global_store_dwordx4 v[142:143], v[138:141], off
	s_nop 1
	v_mov_b32_e32 v138, v201
	v_mov_b32_e32 v139, v201
	v_pk_mul_f32 v[140:141], v[136:137], v[138:139]
	v_pk_mul_f32 v[138:139], v[134:135], v[200:201]
	v_mov_b64_e32 v[134:135], v[138:139]
	v_mov_b64_e32 v[136:137], v[140:141]
	v_mul_f32_e32 v134, 0xbfb8aa3b, v138
	v_mul_f32_e32 v135, 0xbfb8aa3b, v139
	v_mul_f32_e32 v136, 0xbfb8aa3b, v140
	v_mul_f32_e32 v137, 0xbfb8aa3b, v141
	v_exp_f32_e32 v134, v134
	v_exp_f32_e32 v135, v135
	v_exp_f32_e32 v136, v136
	v_exp_f32_e32 v137, v137
	v_add_f32_e32 v134, 1.0, v134
	v_add_f32_e32 v135, 1.0, v135
	v_add_f32_e32 v136, 1.0, v136
	v_add_f32_e32 v137, 1.0, v137
	v_rcp_f32_e32 v134, v134
	v_rcp_f32_e32 v136, v136
	v_rcp_f32_e32 v137, v137
	v_rcp_f32_e32 v135, v135
	v_pk_mul_f32 v[136:137], v[140:141], v[136:137]
	v_pk_mul_f32 v[134:135], v[138:139], v[134:135]
	v_mov_b32_e32 v138, v201
	v_mov_b32_e32 v139, v201
	v_pk_mul_f32 v[132:133], v[132:133], v[138:139]
	v_pk_mul_f32 v[130:131], v[130:131], v[200:201]
	v_mov_b64_e32 v[140:141], v[132:133]
	v_mov_b64_e32 v[138:139], v[130:131]
	v_mul_f32_e32 v138, 0xbfb8aa3b, v130
	v_mul_f32_e32 v139, 0xbfb8aa3b, v131
	v_mul_f32_e32 v140, 0xbfb8aa3b, v132
	v_mul_f32_e32 v141, 0xbfb8aa3b, v133
	v_exp_f32_e32 v138, v138
	v_exp_f32_e32 v139, v139
	v_exp_f32_e32 v140, v140
	v_exp_f32_e32 v141, v141
	v_add_f32_e32 v138, 1.0, v138
	v_add_f32_e32 v139, 1.0, v139
	v_add_f32_e32 v140, 1.0, v140
	v_add_f32_e32 v141, 1.0, v141
	v_rcp_f32_e32 v138, v138
	v_rcp_f32_e32 v140, v140
	v_rcp_f32_e32 v141, v141
	v_rcp_f32_e32 v139, v139
	v_pk_mul_f32 v[140:141], v[132:133], v[140:141]
	v_pk_mul_f32 v[138:139], v[130:131], v[138:139]
	v_cvt_pk_bf16_f32 v130, v134, v135
	v_cvt_pk_bf16_f32 v131, v136, v137
	v_cvt_pk_bf16_f32 v132, v138, v139
	v_cvt_pk_bf16_f32 v133, v140, v141
	global_store_dwordx4 v[142:143], v[130:133], off offset:256
	s_nop 1
	v_pk_mul_f32 v[130:131], v[126:127], v[198:199] op_sel_hi:[1,0]
	v_pk_mul_f32 v[132:133], v[128:129], v[198:199] op_sel_hi:[1,0]
	v_mov_b64_e32 v[126:127], v[130:131]
	v_mov_b64_e32 v[128:129], v[132:133]
	v_mul_f32_e32 v126, 0xbfb8aa3b, v130
	v_mul_f32_e32 v127, 0xbfb8aa3b, v131
	v_mul_f32_e32 v128, 0xbfb8aa3b, v132
	v_mul_f32_e32 v129, 0xbfb8aa3b, v133
	v_exp_f32_e32 v126, v126
	v_exp_f32_e32 v127, v127
	v_exp_f32_e32 v128, v128
	v_exp_f32_e32 v129, v129
	v_add_f32_e32 v126, 1.0, v126
	v_add_f32_e32 v127, 1.0, v127
	v_add_f32_e32 v128, 1.0, v128
	v_add_f32_e32 v129, 1.0, v129
	v_rcp_f32_e32 v126, v126
	v_rcp_f32_e32 v128, v128
	v_rcp_f32_e32 v129, v129
	v_rcp_f32_e32 v127, v127
	v_pk_mul_f32 v[128:129], v[132:133], v[128:129]
	v_pk_mul_f32 v[126:127], v[130:131], v[126:127]
	v_mov_b32_e32 v134, v198
	v_mov_b32_e32 v135, v198
	v_mov_b32_e32 v130, v198
	v_mov_b32_e32 v131, v198
	v_pk_mul_f32 v[124:125], v[124:125], v[130:131]
	v_pk_mul_f32 v[122:123], v[122:123], v[134:135]
	v_mov_b64_e32 v[132:133], v[124:125]
	v_mov_b64_e32 v[130:131], v[122:123]
	v_mul_f32_e32 v130, 0xbfb8aa3b, v122
	v_mul_f32_e32 v131, 0xbfb8aa3b, v123
	v_mul_f32_e32 v132, 0xbfb8aa3b, v124
	v_mul_f32_e32 v133, 0xbfb8aa3b, v125
	v_exp_f32_e32 v130, v130
	v_exp_f32_e32 v131, v131
	v_exp_f32_e32 v132, v132
	v_exp_f32_e32 v133, v133
	v_add_f32_e32 v130, 1.0, v130
	v_add_f32_e32 v131, 1.0, v131
	v_add_f32_e32 v132, 1.0, v132
	v_add_f32_e32 v133, 1.0, v133
	v_rcp_f32_e32 v130, v130
	v_rcp_f32_e32 v132, v132
	v_rcp_f32_e32 v133, v133
	v_rcp_f32_e32 v131, v131
	v_pk_mul_f32 v[132:133], v[124:125], v[132:133]
	v_pk_mul_f32 v[130:131], v[122:123], v[130:131]
	v_add_u32_e32 v124, 32, v192
	v_mad_i64_i32 v[124:125], s[6:7], s56, v124, 0
	v_cvt_pk_bf16_f32 v122, v126, v127
	v_cvt_pk_bf16_f32 v123, v128, v129
	v_lshl_add_u64 v[126:127], v[124:125], 1, v[158:159]
	v_cvt_pk_bf16_f32 v124, v130, v131
	v_cvt_pk_bf16_f32 v125, v132, v133
	global_store_dwordx4 v[126:127], v[122:125], off
	s_nop 1
	v_mov_b32_e32 v122, v198
	v_mov_b32_e32 v123, v198
	v_pk_mul_f32 v[124:125], v[120:121], v[122:123]
	v_pk_mul_f32 v[122:123], v[118:119], v[134:135]
	v_mov_b64_e32 v[118:119], v[122:123]
	v_mov_b64_e32 v[120:121], v[124:125]
	v_mul_f32_e32 v118, 0xbfb8aa3b, v122
	v_mul_f32_e32 v119, 0xbfb8aa3b, v123
	v_mul_f32_e32 v120, 0xbfb8aa3b, v124
	v_mul_f32_e32 v121, 0xbfb8aa3b, v125
	v_exp_f32_e32 v118, v118
	v_exp_f32_e32 v119, v119
	v_exp_f32_e32 v120, v120
	v_exp_f32_e32 v121, v121
	v_add_f32_e32 v118, 1.0, v118
	v_add_f32_e32 v119, 1.0, v119
	v_add_f32_e32 v120, 1.0, v120
	v_add_f32_e32 v121, 1.0, v121
	v_rcp_f32_e32 v118, v118
	v_rcp_f32_e32 v120, v120
	v_rcp_f32_e32 v121, v121
	v_rcp_f32_e32 v119, v119
	v_pk_mul_f32 v[120:121], v[124:125], v[120:121]
	v_pk_mul_f32 v[118:119], v[122:123], v[118:119]
	v_mov_b32_e32 v122, v198
	v_mov_b32_e32 v123, v198
	v_pk_mul_f32 v[116:117], v[116:117], v[122:123]
	v_pk_mul_f32 v[114:115], v[114:115], v[134:135]
	v_mov_b64_e32 v[124:125], v[116:117]
	v_mov_b64_e32 v[122:123], v[114:115]
	v_mul_f32_e32 v122, 0xbfb8aa3b, v114
	v_mul_f32_e32 v123, 0xbfb8aa3b, v115
	v_mul_f32_e32 v124, 0xbfb8aa3b, v116
	v_mul_f32_e32 v125, 0xbfb8aa3b, v117
	v_exp_f32_e32 v122, v122
	v_exp_f32_e32 v123, v123
	v_exp_f32_e32 v124, v124
	v_exp_f32_e32 v125, v125
	v_add_f32_e32 v122, 1.0, v122
; __device__ __forceinline__ float fsilu(float x) { return x * __builtin_amdgcn_rcpf(1.f + __expf(-x)); }
;     __device__ __forceinline__ void operator()(const f32x4 (&acc)[2][2][4][2], const pg8::Unit& u, int wr, int wc, int fr, int fq) const {
;     ...
;                 for (int m = 0; m < 4; ++m) { const int r = rowb + ai * 128 + m * 16; const float sc = rs[ai][m];
; #pragma unroll
;                     for (int bj = 0; bj < 2; ++bj) { u32x4 w;
; #pragma unroll
;                         for (int n = 0; n < 2; ++n) { f32x4 v = acc[ai][bj][m][n] * sc;
;                             if (cat == 0) v = v * QSCALE; else if (cat != 6) { v[0] = fsilu(v[0]); v[1] = fsilu(v[1]); v[2] = fsilu(v[2]); v[3] = fsilu(v[3]); }
;                             w[2 * n] = pk2(v[0], v[1]); w[2 * n + 1] = pk2(v[2], v[3]); }
;                         *(u32x4*)(base + (size_t)r * pitch + cb + bj * 128) = w; } }
	v_add_f32_e32 v123, 1.0, v123
	v_add_f32_e32 v124, 1.0, v124
	v_add_f32_e32 v125, 1.0, v125
	v_rcp_f32_e32 v122, v122
	v_rcp_f32_e32 v124, v124
	v_rcp_f32_e32 v125, v125
	v_rcp_f32_e32 v123, v123
	v_pk_mul_f32 v[124:125], v[116:117], v[124:125]
	v_pk_mul_f32 v[122:123], v[114:115], v[122:123]
	v_cvt_pk_bf16_f32 v114, v118, v119
	v_cvt_pk_bf16_f32 v115, v120, v121
	v_cvt_pk_bf16_f32 v116, v122, v123
	v_cvt_pk_bf16_f32 v117, v124, v125
	global_store_dwordx4 v[126:127], v[114:117], off offset:256
	s_nop 1
	v_pk_mul_f32 v[114:115], v[106:107], v[198:199] op_sel:[0,1]
	v_pk_mul_f32 v[116:117], v[108:109], v[198:199] op_sel:[0,1]
	v_mov_b64_e32 v[106:107], v[114:115]
	v_mov_b64_e32 v[108:109], v[116:117]
	v_mul_f32_e32 v106, 0xbfb8aa3b, v114
	v_mul_f32_e32 v107, 0xbfb8aa3b, v115
	v_mul_f32_e32 v108, 0xbfb8aa3b, v116
	v_mul_f32_e32 v109, 0xbfb8aa3b, v117
	v_exp_f32_e32 v106, v106
	v_exp_f32_e32 v107, v107
	v_exp_f32_e32 v108, v108
	v_exp_f32_e32 v109, v109
	v_add_f32_e32 v106, 1.0, v106
	v_add_f32_e32 v107, 1.0, v107
	v_add_f32_e32 v108, 1.0, v108
	v_add_f32_e32 v109, 1.0, v109
	v_rcp_f32_e32 v106, v106
	v_rcp_f32_e32 v108, v108
	v_rcp_f32_e32 v109, v109
	v_rcp_f32_e32 v107, v107
	v_pk_mul_f32 v[108:109], v[116:117], v[108:109]
	v_pk_mul_f32 v[106:107], v[114:115], v[106:107]
	v_mov_b32_e32 v198, v199
	v_mov_b32_e32 v114, v199
	v_mov_b32_e32 v115, v199
	v_pk_mul_f32 v[88:89], v[88:89], v[114:115]
	v_pk_mul_f32 v[86:87], v[86:87], v[198:199]
	v_mov_b64_e32 v[116:117], v[88:89]
	v_mov_b64_e32 v[114:115], v[86:87]
	v_mul_f32_e32 v114, 0xbfb8aa3b, v86
	v_mul_f32_e32 v115, 0xbfb8aa3b, v87
	v_mul_f32_e32 v116, 0xbfb8aa3b, v88
	v_mul_f32_e32 v117, 0xbfb8aa3b, v89
	v_exp_f32_e32 v114, v114
	v_exp_f32_e32 v115, v115
	v_exp_f32_e32 v116, v116
	v_exp_f32_e32 v117, v117
	v_add_f32_e32 v114, 1.0, v114
	v_add_f32_e32 v115, 1.0, v115
	v_add_f32_e32 v116, 1.0, v116
	v_add_f32_e32 v117, 1.0, v117
	v_rcp_f32_e32 v114, v114
	v_rcp_f32_e32 v116, v116
	v_rcp_f32_e32 v117, v117
	v_rcp_f32_e32 v115, v115
	v_pk_mul_f32 v[116:117], v[88:89], v[116:117]
	v_pk_mul_f32 v[114:115], v[86:87], v[114:115]
	v_add_u32_e32 v88, 48, v192
	v_mad_i64_i32 v[88:89], s[6:7], s56, v88, 0
	v_cvt_pk_bf16_f32 v86, v106, v107
	v_cvt_pk_bf16_f32 v87, v108, v109
	v_lshl_add_u64 v[106:107], v[88:89], 1, v[158:159]
	v_cvt_pk_bf16_f32 v88, v114, v115
	v_cvt_pk_bf16_f32 v89, v116, v117
	global_store_dwordx4 v[106:107], v[86:89], off
	s_nop 1
	v_mov_b32_e32 v86, v199
	v_mov_b32_e32 v87, v199
	v_pk_mul_f32 v[88:89], v[72:73], v[86:87]
	v_pk_mul_f32 v[86:87], v[70:71], v[198:199]
	v_mov_b64_e32 v[70:71], v[86:87]
	v_mov_b64_e32 v[72:73], v[88:89]
	v_mul_f32_e32 v70, 0xbfb8aa3b, v86
	v_mul_f32_e32 v71, 0xbfb8aa3b, v87
	v_mul_f32_e32 v72, 0xbfb8aa3b, v88
	v_mul_f32_e32 v73, 0xbfb8aa3b, v89
	v_exp_f32_e32 v70, v70
	v_exp_f32_e32 v71, v71
	v_exp_f32_e32 v72, v72
	v_exp_f32_e32 v73, v73
	v_add_f32_e32 v70, 1.0, v70
	v_add_f32_e32 v71, 1.0, v71
	v_add_f32_e32 v72, 1.0, v72
	v_add_f32_e32 v73, 1.0, v73
	v_rcp_f32_e32 v70, v70
	v_rcp_f32_e32 v72, v72
	v_rcp_f32_e32 v73, v73
	v_rcp_f32_e32 v71, v71
	v_pk_mul_f32 v[72:73], v[88:89], v[72:73]
	v_pk_mul_f32 v[70:71], v[86:87], v[70:71]
	v_mov_b32_e32 v86, v199
	v_mov_b32_e32 v87, v199
	v_pk_mul_f32 v[68:69], v[68:69], v[86:87]
	v_pk_mul_f32 v[66:67], v[66:67], v[198:199]
	v_mov_b64_e32 v[88:89], v[68:69]
	v_mov_b64_e32 v[86:87], v[66:67]
	v_mul_f32_e32 v86, 0xbfb8aa3b, v66
	v_mul_f32_e32 v87, 0xbfb8aa3b, v67
	v_mul_f32_e32 v88, 0xbfb8aa3b, v68
	v_mul_f32_e32 v89, 0xbfb8aa3b, v69
	v_exp_f32_e32 v86, v86
	v_exp_f32_e32 v87, v87
	v_exp_f32_e32 v88, v88
	v_exp_f32_e32 v89, v89
	v_add_f32_e32 v86, 1.0, v86
	v_add_f32_e32 v87, 1.0, v87
	v_add_f32_e32 v88, 1.0, v88
	v_add_f32_e32 v89, 1.0, v89
	v_rcp_f32_e32 v86, v86
	v_rcp_f32_e32 v88, v88
	v_rcp_f32_e32 v89, v89
	v_rcp_f32_e32 v87, v87
	v_pk_mul_f32 v[88:89], v[68:69], v[88:89]
	v_pk_mul_f32 v[86:87], v[66:67], v[86:87]
	v_cvt_pk_bf16_f32 v66, v70, v71
	v_cvt_pk_bf16_f32 v67, v72, v73
	v_cvt_pk_bf16_f32 v68, v86, v87
	v_cvt_pk_bf16_f32 v69, v88, v89
	global_store_dwordx4 v[106:107], v[66:69], off offset:256
	s_nop 1
	v_pk_mul_f32 v[66:67], v[62:63], v[196:197] op_sel_hi:[1,0]
	v_pk_mul_f32 v[68:69], v[64:65], v[196:197] op_sel_hi:[1,0]
	v_mov_b64_e32 v[62:63], v[66:67]
	v_mov_b64_e32 v[64:65], v[68:69]
	v_mul_f32_e32 v62, 0xbfb8aa3b, v66
	v_mul_f32_e32 v63, 0xbfb8aa3b, v67
	v_mul_f32_e32 v64, 0xbfb8aa3b, v68
	v_mul_f32_e32 v65, 0xbfb8aa3b, v69
	v_exp_f32_e32 v62, v62
	v_exp_f32_e32 v63, v63
	v_exp_f32_e32 v64, v64
	v_exp_f32_e32 v65, v65
	v_add_f32_e32 v62, 1.0, v62
	v_add_f32_e32 v63, 1.0, v63
	v_add_f32_e32 v64, 1.0, v64
	v_add_f32_e32 v65, 1.0, v65
	v_rcp_f32_e32 v62, v62
	v_rcp_f32_e32 v64, v64
	v_rcp_f32_e32 v65, v65
	v_rcp_f32_e32 v63, v63
	v_pk_mul_f32 v[64:65], v[68:69], v[64:65]
	v_pk_mul_f32 v[62:63], v[66:67], v[62:63]
	v_mov_b32_e32 v70, v196
	v_mov_b32_e32 v71, v196
	v_mov_b32_e32 v66, v196
	v_mov_b32_e32 v67, v196
	v_pk_mul_f32 v[60:61], v[60:61], v[66:67]
	v_pk_mul_f32 v[58:59], v[58:59], v[70:71]
	v_mov_b64_e32 v[68:69], v[60:61]
	v_mov_b64_e32 v[66:67], v[58:59]
	v_mul_f32_e32 v66, 0xbfb8aa3b, v58
	v_mul_f32_e32 v67, 0xbfb8aa3b, v59
	v_mul_f32_e32 v68, 0xbfb8aa3b, v60
	v_mul_f32_e32 v69, 0xbfb8aa3b, v61
	v_exp_f32_e32 v66, v66
	v_exp_f32_e32 v67, v67
	v_exp_f32_e32 v68, v68
	v_exp_f32_e32 v69, v69
	v_add_f32_e32 v66, 1.0, v66
	v_add_f32_e32 v67, 1.0, v67
	v_add_f32_e32 v68, 1.0, v68
	v_add_f32_e32 v69, 1.0, v69
	v_rcp_f32_e32 v66, v66
	v_rcp_f32_e32 v68, v68
	v_rcp_f32_e32 v69, v69
	v_rcp_f32_e32 v67, v67
	v_pk_mul_f32 v[68:69], v[60:61], v[68:69]
	v_pk_mul_f32 v[66:67], v[58:59], v[66:67]
; __device__ __forceinline__ float fsilu(float x) { return x * __builtin_amdgcn_rcpf(1.f + __expf(-x)); }
;     __device__ __forceinline__ void operator()(const f32x4 (&acc)[2][2][4][2], const pg8::Unit& u, int wr, int wc, int fr, int fq) const {
;     ...
;                 for (int m = 0; m < 4; ++m) { const int r = rowb + ai * 128 + m * 16; const float sc = rs[ai][m];
; #pragma unroll
;                     for (int bj = 0; bj < 2; ++bj) { u32x4 w;
; #pragma unroll
;                         for (int n = 0; n < 2; ++n) { f32x4 v = acc[ai][bj][m][n] * sc;
;                             if (cat == 0) v = v * QSCALE; else if (cat != 6) { v[0] = fsilu(v[0]); v[1] = fsilu(v[1]); v[2] = fsilu(v[2]); v[3] = fsilu(v[3]); }
;                             w[2 * n] = pk2(v[0], v[1]); w[2 * n + 1] = pk2(v[2], v[3]); }
;                         *(u32x4*)(base + (size_t)r * pitch + cb + bj * 128) = w; } }
	v_add_u32_e32 v60, 0x80, v192
	v_mad_i64_i32 v[60:61], s[6:7], s56, v60, 0
	v_cvt_pk_bf16_f32 v58, v62, v63
	v_cvt_pk_bf16_f32 v59, v64, v65
	v_lshl_add_u64 v[62:63], v[60:61], 1, v[158:159]
	v_cvt_pk_bf16_f32 v60, v66, v67
	v_cvt_pk_bf16_f32 v61, v68, v69
	global_store_dwordx4 v[62:63], v[58:61], off
	s_nop 1
	v_mov_b32_e32 v58, v196
	v_mov_b32_e32 v59, v196
	v_pk_mul_f32 v[60:61], v[56:57], v[58:59]
	v_pk_mul_f32 v[58:59], v[54:55], v[70:71]
	v_mov_b64_e32 v[54:55], v[58:59]
	v_mov_b64_e32 v[56:57], v[60:61]
	v_mul_f32_e32 v54, 0xbfb8aa3b, v58
	v_mul_f32_e32 v55, 0xbfb8aa3b, v59
	v_mul_f32_e32 v56, 0xbfb8aa3b, v60
	v_mul_f32_e32 v57, 0xbfb8aa3b, v61
	v_exp_f32_e32 v54, v54
	v_exp_f32_e32 v55, v55
	v_exp_f32_e32 v56, v56
	v_exp_f32_e32 v57, v57
	v_add_f32_e32 v54, 1.0, v54
	v_add_f32_e32 v55, 1.0, v55
	v_add_f32_e32 v56, 1.0, v56
	v_add_f32_e32 v57, 1.0, v57
	v_rcp_f32_e32 v54, v54
	v_rcp_f32_e32 v56, v56
	v_rcp_f32_e32 v57, v57
	v_rcp_f32_e32 v55, v55
	v_pk_mul_f32 v[56:57], v[60:61], v[56:57]
	v_pk_mul_f32 v[54:55], v[58:59], v[54:55]
	v_mov_b32_e32 v58, v196
	v_mov_b32_e32 v59, v196
	v_pk_mul_f32 v[52:53], v[52:53], v[58:59]
	v_pk_mul_f32 v[50:51], v[50:51], v[70:71]
	v_mov_b64_e32 v[60:61], v[52:53]
	v_mov_b64_e32 v[58:59], v[50:51]
	v_mul_f32_e32 v58, 0xbfb8aa3b, v50
	v_mul_f32_e32 v59, 0xbfb8aa3b, v51
	v_mul_f32_e32 v60, 0xbfb8aa3b, v52
	v_mul_f32_e32 v61, 0xbfb8aa3b, v53
	v_exp_f32_e32 v58, v58
	v_exp_f32_e32 v59, v59
	v_exp_f32_e32 v60, v60
	v_exp_f32_e32 v61, v61
	v_add_f32_e32 v58, 1.0, v58
	v_add_f32_e32 v59, 1.0, v59
	v_add_f32_e32 v60, 1.0, v60
	v_add_f32_e32 v61, 1.0, v61
	v_rcp_f32_e32 v58, v58
	v_rcp_f32_e32 v60, v60
	v_rcp_f32_e32 v61, v61
	v_rcp_f32_e32 v59, v59
	v_pk_mul_f32 v[60:61], v[52:53], v[60:61]
	v_pk_mul_f32 v[58:59], v[50:51], v[58:59]
	v_cvt_pk_bf16_f32 v50, v54, v55
	v_cvt_pk_bf16_f32 v51, v56, v57
	v_cvt_pk_bf16_f32 v52, v58, v59
	v_cvt_pk_bf16_f32 v53, v60, v61
	global_store_dwordx4 v[62:63], v[50:53], off offset:256
	s_nop 1
	v_pk_mul_f32 v[50:51], v[46:47], v[196:197] op_sel:[0,1]
	v_pk_mul_f32 v[52:53], v[48:49], v[196:197] op_sel:[0,1]
	v_mov_b64_e32 v[46:47], v[50:51]
	v_mov_b64_e32 v[48:49], v[52:53]
	v_mul_f32_e32 v46, 0xbfb8aa3b, v50
	v_mul_f32_e32 v47, 0xbfb8aa3b, v51
	v_mul_f32_e32 v48, 0xbfb8aa3b, v52
	v_mul_f32_e32 v49, 0xbfb8aa3b, v53
	v_exp_f32_e32 v46, v46
	v_exp_f32_e32 v47, v47
	v_exp_f32_e32 v48, v48
	v_exp_f32_e32 v49, v49
	v_add_f32_e32 v46, 1.0, v46
	v_add_f32_e32 v47, 1.0, v47
	v_add_f32_e32 v48, 1.0, v48
	v_add_f32_e32 v49, 1.0, v49
	v_rcp_f32_e32 v46, v46
	v_rcp_f32_e32 v48, v48
	v_rcp_f32_e32 v49, v49
	v_rcp_f32_e32 v47, v47
	v_pk_mul_f32 v[48:49], v[52:53], v[48:49]
	v_pk_mul_f32 v[46:47], v[50:51], v[46:47]
	v_mov_b32_e32 v196, v197
	v_mov_b32_e32 v50, v197
	v_mov_b32_e32 v51, v197
	v_pk_mul_f32 v[44:45], v[44:45], v[50:51]
	v_pk_mul_f32 v[42:43], v[42:43], v[196:197]
	v_mov_b64_e32 v[52:53], v[44:45]
	v_mov_b64_e32 v[50:51], v[42:43]
	v_mul_f32_e32 v50, 0xbfb8aa3b, v42
	v_mul_f32_e32 v51, 0xbfb8aa3b, v43
	v_mul_f32_e32 v52, 0xbfb8aa3b, v44
	v_mul_f32_e32 v53, 0xbfb8aa3b, v45
	v_exp_f32_e32 v50, v50
	v_exp_f32_e32 v51, v51
	v_exp_f32_e32 v52, v52
	v_exp_f32_e32 v53, v53
	v_add_f32_e32 v50, 1.0, v50
	v_add_f32_e32 v51, 1.0, v51
	v_add_f32_e32 v52, 1.0, v52
	v_add_f32_e32 v53, 1.0, v53
	v_rcp_f32_e32 v50, v50
	v_rcp_f32_e32 v52, v52
	v_rcp_f32_e32 v53, v53
	v_rcp_f32_e32 v51, v51
	v_pk_mul_f32 v[52:53], v[44:45], v[52:53]
	v_pk_mul_f32 v[50:51], v[42:43], v[50:51]
	v_add_u32_e32 v44, 0x90, v192
	v_mad_i64_i32 v[44:45], s[6:7], s56, v44, 0
	v_cvt_pk_bf16_f32 v42, v46, v47
	v_cvt_pk_bf16_f32 v43, v48, v49
	v_lshl_add_u64 v[46:47], v[44:45], 1, v[158:159]
	v_cvt_pk_bf16_f32 v44, v50, v51
	v_cvt_pk_bf16_f32 v45, v52, v53
	global_store_dwordx4 v[46:47], v[42:45], off
	s_nop 1
	v_mov_b32_e32 v42, v197
	v_mov_b32_e32 v43, v197
	v_pk_mul_f32 v[44:45], v[40:41], v[42:43]
	v_pk_mul_f32 v[42:43], v[38:39], v[196:197]
	v_mov_b64_e32 v[38:39], v[42:43]
	v_mov_b64_e32 v[40:41], v[44:45]
	v_mul_f32_e32 v38, 0xbfb8aa3b, v42
	v_mul_f32_e32 v39, 0xbfb8aa3b, v43
	v_mul_f32_e32 v40, 0xbfb8aa3b, v44
	v_mul_f32_e32 v41, 0xbfb8aa3b, v45
	v_exp_f32_e32 v38, v38
	v_exp_f32_e32 v39, v39
	v_exp_f32_e32 v40, v40
	v_exp_f32_e32 v41, v41
	v_add_f32_e32 v38, 1.0, v38
	v_add_f32_e32 v39, 1.0, v39
	v_add_f32_e32 v40, 1.0, v40
	v_add_f32_e32 v41, 1.0, v41
	v_rcp_f32_e32 v38, v38
	v_rcp_f32_e32 v40, v40
	v_rcp_f32_e32 v41, v41
	v_rcp_f32_e32 v39, v39
	v_pk_mul_f32 v[40:41], v[44:45], v[40:41]
	v_pk_mul_f32 v[38:39], v[42:43], v[38:39]
	v_mov_b32_e32 v42, v197
	v_mov_b32_e32 v43, v197
	v_pk_mul_f32 v[36:37], v[36:37], v[42:43]
	v_pk_mul_f32 v[34:35], v[34:35], v[196:197]
	v_mov_b64_e32 v[44:45], v[36:37]
	v_mov_b64_e32 v[42:43], v[34:35]
	v_mul_f32_e32 v42, 0xbfb8aa3b, v34
	v_mul_f32_e32 v43, 0xbfb8aa3b, v35
	v_mul_f32_e32 v44, 0xbfb8aa3b, v36
	v_mul_f32_e32 v45, 0xbfb8aa3b, v37
	v_exp_f32_e32 v42, v42
	v_exp_f32_e32 v43, v43
	v_exp_f32_e32 v44, v44
	v_exp_f32_e32 v45, v45
	v_add_f32_e32 v42, 1.0, v42
	v_add_f32_e32 v43, 1.0, v43
	v_add_f32_e32 v44, 1.0, v44
	v_add_f32_e32 v45, 1.0, v45
	v_rcp_f32_e32 v42, v42
	v_rcp_f32_e32 v44, v44
	v_rcp_f32_e32 v45, v45
	v_rcp_f32_e32 v43, v43
	v_pk_mul_f32 v[44:45], v[36:37], v[44:45]
	v_pk_mul_f32 v[42:43], v[34:35], v[42:43]
	v_cvt_pk_bf16_f32 v34, v38, v39
	v_cvt_pk_bf16_f32 v35, v40, v41
	v_cvt_pk_bf16_f32 v36, v42, v43
	v_cvt_pk_bf16_f32 v37, v44, v45
	global_store_dwordx4 v[46:47], v[34:37], off offset:256
	s_nop 1
	v_pk_mul_f32 v[34:35], v[30:31], v[194:195] op_sel_hi:[1,0]
	v_pk_mul_f32 v[36:37], v[32:33], v[194:195] op_sel_hi:[1,0]
	v_mov_b64_e32 v[30:31], v[34:35]
; __device__ __forceinline__ float fsilu(float x) { return x * __builtin_amdgcn_rcpf(1.f + __expf(-x)); }
;     __device__ __forceinline__ void operator()(const f32x4 (&acc)[2][2][4][2], const pg8::Unit& u, int wr, int wc, int fr, int fq) const {
;     ...
;                 for (int m = 0; m < 4; ++m) { const int r = rowb + ai * 128 + m * 16; const float sc = rs[ai][m];
; #pragma unroll
;                     for (int bj = 0; bj < 2; ++bj) { u32x4 w;
; #pragma unroll
;                         for (int n = 0; n < 2; ++n) { f32x4 v = acc[ai][bj][m][n] * sc;
;                             if (cat == 0) v = v * QSCALE; else if (cat != 6) { v[0] = fsilu(v[0]); v[1] = fsilu(v[1]); v[2] = fsilu(v[2]); v[3] = fsilu(v[3]); }
;                             w[2 * n] = pk2(v[0], v[1]); w[2 * n + 1] = pk2(v[2], v[3]); }
;                         *(u32x4*)(base + (size_t)r * pitch + cb + bj * 128) = w; } }
	v_mov_b64_e32 v[32:33], v[36:37]
	v_mul_f32_e32 v30, 0xbfb8aa3b, v34
	v_mul_f32_e32 v31, 0xbfb8aa3b, v35
	v_mul_f32_e32 v32, 0xbfb8aa3b, v36
	v_mul_f32_e32 v33, 0xbfb8aa3b, v37
	v_exp_f32_e32 v30, v30
	v_exp_f32_e32 v31, v31
	v_exp_f32_e32 v32, v32
	v_exp_f32_e32 v33, v33
	v_add_f32_e32 v30, 1.0, v30
	v_add_f32_e32 v31, 1.0, v31
	v_add_f32_e32 v32, 1.0, v32
	v_add_f32_e32 v33, 1.0, v33
	v_rcp_f32_e32 v30, v30
	v_rcp_f32_e32 v32, v32
	v_rcp_f32_e32 v33, v33
	v_rcp_f32_e32 v31, v31
	v_pk_mul_f32 v[32:33], v[36:37], v[32:33]
	v_pk_mul_f32 v[30:31], v[34:35], v[30:31]
	v_mov_b32_e32 v38, v194
	v_mov_b32_e32 v39, v194
	v_mov_b32_e32 v34, v194
	v_mov_b32_e32 v35, v194
	v_pk_mul_f32 v[28:29], v[28:29], v[34:35]
	v_pk_mul_f32 v[26:27], v[26:27], v[38:39]
	v_mov_b64_e32 v[36:37], v[28:29]
	v_mov_b64_e32 v[34:35], v[26:27]
	v_mul_f32_e32 v34, 0xbfb8aa3b, v26
	v_mul_f32_e32 v35, 0xbfb8aa3b, v27
	v_mul_f32_e32 v36, 0xbfb8aa3b, v28
	v_mul_f32_e32 v37, 0xbfb8aa3b, v29
	v_exp_f32_e32 v34, v34
	v_exp_f32_e32 v35, v35
	v_exp_f32_e32 v36, v36
	v_exp_f32_e32 v37, v37
	v_add_f32_e32 v34, 1.0, v34
	v_add_f32_e32 v35, 1.0, v35
	v_add_f32_e32 v36, 1.0, v36
	v_add_f32_e32 v37, 1.0, v37
	v_rcp_f32_e32 v34, v34
	v_rcp_f32_e32 v36, v36
	v_rcp_f32_e32 v37, v37
	v_rcp_f32_e32 v35, v35
	v_pk_mul_f32 v[36:37], v[28:29], v[36:37]
	v_pk_mul_f32 v[34:35], v[26:27], v[34:35]
	v_add_u32_e32 v28, 0xa0, v192
	v_mad_i64_i32 v[28:29], s[6:7], s56, v28, 0
	v_cvt_pk_bf16_f32 v26, v30, v31
	v_cvt_pk_bf16_f32 v27, v32, v33
	v_lshl_add_u64 v[30:31], v[28:29], 1, v[158:159]
	v_cvt_pk_bf16_f32 v28, v34, v35
	v_cvt_pk_bf16_f32 v29, v36, v37
	global_store_dwordx4 v[30:31], v[26:29], off
	s_nop 1
	v_mov_b32_e32 v26, v194
	v_mov_b32_e32 v27, v194
	v_pk_mul_f32 v[28:29], v[24:25], v[26:27]
	v_pk_mul_f32 v[26:27], v[22:23], v[38:39]
	v_mov_b64_e32 v[22:23], v[26:27]
	v_mov_b64_e32 v[24:25], v[28:29]
	v_mul_f32_e32 v22, 0xbfb8aa3b, v26
	v_mul_f32_e32 v23, 0xbfb8aa3b, v27
	v_mul_f32_e32 v24, 0xbfb8aa3b, v28
	v_mul_f32_e32 v25, 0xbfb8aa3b, v29
	v_exp_f32_e32 v22, v22
	v_exp_f32_e32 v23, v23
	v_exp_f32_e32 v24, v24
	v_exp_f32_e32 v25, v25
	v_add_f32_e32 v22, 1.0, v22
	v_add_f32_e32 v23, 1.0, v23
	v_add_f32_e32 v24, 1.0, v24
	v_add_f32_e32 v25, 1.0, v25
	v_rcp_f32_e32 v22, v22
	v_rcp_f32_e32 v24, v24
	v_rcp_f32_e32 v25, v25
	v_rcp_f32_e32 v23, v23
	v_pk_mul_f32 v[24:25], v[28:29], v[24:25]
	v_pk_mul_f32 v[22:23], v[26:27], v[22:23]
	v_mov_b32_e32 v26, v194
	v_mov_b32_e32 v27, v194
	v_pk_mul_f32 v[20:21], v[20:21], v[26:27]
	v_pk_mul_f32 v[18:19], v[18:19], v[38:39]
	v_mov_b64_e32 v[28:29], v[20:21]
	v_mov_b64_e32 v[26:27], v[18:19]
	v_mul_f32_e32 v26, 0xbfb8aa3b, v18
	v_mul_f32_e32 v27, 0xbfb8aa3b, v19
	v_mul_f32_e32 v28, 0xbfb8aa3b, v20
	v_mul_f32_e32 v29, 0xbfb8aa3b, v21
	v_exp_f32_e32 v26, v26
	v_exp_f32_e32 v27, v27
	v_exp_f32_e32 v28, v28
	v_exp_f32_e32 v29, v29
	v_add_f32_e32 v26, 1.0, v26
	v_add_f32_e32 v27, 1.0, v27
	v_add_f32_e32 v28, 1.0, v28
	v_add_f32_e32 v29, 1.0, v29
	v_rcp_f32_e32 v26, v26
	v_rcp_f32_e32 v28, v28
	v_rcp_f32_e32 v29, v29
	v_rcp_f32_e32 v27, v27
	v_pk_mul_f32 v[28:29], v[20:21], v[28:29]
	v_pk_mul_f32 v[26:27], v[18:19], v[26:27]
	v_cvt_pk_bf16_f32 v18, v22, v23
	v_cvt_pk_bf16_f32 v19, v24, v25
	v_cvt_pk_bf16_f32 v20, v26, v27
	v_cvt_pk_bf16_f32 v21, v28, v29
	global_store_dwordx4 v[30:31], v[18:21], off offset:256
	s_nop 1
	v_pk_mul_f32 v[18:19], v[14:15], v[194:195] op_sel:[0,1]
	v_pk_mul_f32 v[20:21], v[16:17], v[194:195] op_sel:[0,1]
	v_mov_b64_e32 v[14:15], v[18:19]
	v_mov_b64_e32 v[16:17], v[20:21]
	v_mul_f32_e32 v14, 0xbfb8aa3b, v18
	v_mul_f32_e32 v15, 0xbfb8aa3b, v19
	v_mul_f32_e32 v16, 0xbfb8aa3b, v20
	v_mul_f32_e32 v17, 0xbfb8aa3b, v21
	v_exp_f32_e32 v14, v14
	v_exp_f32_e32 v15, v15
	v_exp_f32_e32 v16, v16
	v_exp_f32_e32 v17, v17
	v_add_f32_e32 v14, 1.0, v14
	v_add_f32_e32 v15, 1.0, v15
	v_add_f32_e32 v16, 1.0, v16
	v_add_f32_e32 v17, 1.0, v17
	v_rcp_f32_e32 v14, v14
	v_rcp_f32_e32 v16, v16
	v_rcp_f32_e32 v17, v17
	v_rcp_f32_e32 v15, v15
	v_pk_mul_f32 v[16:17], v[20:21], v[16:17]
	v_pk_mul_f32 v[14:15], v[18:19], v[14:15]
	v_mov_b32_e32 v194, v195
	v_mov_b32_e32 v18, v195
	v_mov_b32_e32 v19, v195
	v_pk_mul_f32 v[12:13], v[12:13], v[18:19]
	v_pk_mul_f32 v[10:11], v[10:11], v[194:195]
	v_mov_b64_e32 v[20:21], v[12:13]
	v_mov_b64_e32 v[18:19], v[10:11]
	v_mul_f32_e32 v18, 0xbfb8aa3b, v10
	v_mul_f32_e32 v19, 0xbfb8aa3b, v11
	v_mul_f32_e32 v20, 0xbfb8aa3b, v12
	v_mul_f32_e32 v21, 0xbfb8aa3b, v13
	v_exp_f32_e32 v18, v18
	v_exp_f32_e32 v19, v19
	v_exp_f32_e32 v20, v20
	v_exp_f32_e32 v21, v21
	v_add_f32_e32 v18, 1.0, v18
	v_add_f32_e32 v19, 1.0, v19
	v_add_f32_e32 v20, 1.0, v20
	v_add_f32_e32 v21, 1.0, v21
	v_rcp_f32_e32 v18, v18
	v_rcp_f32_e32 v20, v20
	v_rcp_f32_e32 v21, v21
	v_rcp_f32_e32 v19, v19
	v_pk_mul_f32 v[20:21], v[12:13], v[20:21]
	v_pk_mul_f32 v[18:19], v[10:11], v[18:19]
	v_add_u32_e32 v12, 0xb0, v192
	v_mad_i64_i32 v[12:13], s[6:7], s56, v12, 0
	v_cvt_pk_bf16_f32 v10, v14, v15
	v_cvt_pk_bf16_f32 v11, v16, v17
	v_lshl_add_u64 v[14:15], v[12:13], 1, v[158:159]
	v_cvt_pk_bf16_f32 v12, v18, v19
	v_cvt_pk_bf16_f32 v13, v20, v21
	global_store_dwordx4 v[14:15], v[10:13], off
	s_nop 1
	v_mov_b32_e32 v10, v195
	v_mov_b32_e32 v11, v195
	v_pk_mul_f32 v[12:13], v[8:9], v[10:11]
	v_pk_mul_f32 v[10:11], v[6:7], v[194:195]
	v_mov_b64_e32 v[6:7], v[10:11]
	v_mov_b64_e32 v[8:9], v[12:13]
	v_mul_f32_e32 v6, 0xbfb8aa3b, v10
	v_mul_f32_e32 v7, 0xbfb8aa3b, v11
	v_mul_f32_e32 v8, 0xbfb8aa3b, v12
	v_mul_f32_e32 v9, 0xbfb8aa3b, v13
	v_exp_f32_e32 v6, v6
	v_exp_f32_e32 v7, v7
	v_exp_f32_e32 v8, v8
	v_exp_f32_e32 v9, v9
	v_add_f32_e32 v6, 1.0, v6
	v_add_f32_e32 v7, 1.0, v7
	v_add_f32_e32 v8, 1.0, v8
	v_add_f32_e32 v9, 1.0, v9
	v_rcp_f32_e32 v6, v6
	v_rcp_f32_e32 v8, v8
	v_rcp_f32_e32 v9, v9
	v_rcp_f32_e32 v7, v7
	v_pk_mul_f32 v[8:9], v[12:13], v[8:9]
	v_pk_mul_f32 v[6:7], v[10:11], v[6:7]
	v_mov_b32_e32 v10, v195
	v_mov_b32_e32 v11, v195
	v_pk_mul_f32 v[4:5], v[4:5], v[10:11]
	v_pk_mul_f32 v[2:3], v[2:3], v[194:195]
	v_mov_b64_e32 v[12:13], v[4:5]
	v_mov_b64_e32 v[10:11], v[2:3]
	v_mul_f32_e32 v10, 0xbfb8aa3b, v2
	v_mul_f32_e32 v11, 0xbfb8aa3b, v3
	v_mul_f32_e32 v12, 0xbfb8aa3b, v4
	v_mul_f32_e32 v13, 0xbfb8aa3b, v5
	v_exp_f32_e32 v10, v10
	v_exp_f32_e32 v11, v11
	v_exp_f32_e32 v12, v12
	v_exp_f32_e32 v13, v13
	v_add_f32_e32 v10, 1.0, v10
	v_add_f32_e32 v11, 1.0, v11
	v_add_f32_e32 v12, 1.0, v12
	v_add_f32_e32 v13, 1.0, v13
	v_rcp_f32_e32 v10, v10
	v_rcp_f32_e32 v12, v12
	v_rcp_f32_e32 v13, v13
	v_rcp_f32_e32 v11, v11
	v_pk_mul_f32 v[12:13], v[4:5], v[12:13]
	v_pk_mul_f32 v[10:11], v[2:3], v[10:11]
	v_cvt_pk_bf16_f32 v2, v6, v7
	v_cvt_pk_bf16_f32 v3, v8, v9
	v_cvt_pk_bf16_f32 v4, v10, v11
	v_cvt_pk_bf16_f32 v5, v12, v13
	global_store_dwordx4 v[14:15], v[2:5], off offset:256
	s_nop 1
	s_branch .Lbf16_join
; __device__ __forceinline__ float fsilu(float x) { return x * __builtin_amdgcn_rcpf(1.f + __expf(-x)); }
;     __device__ __forceinline__ void operator()(const f32x4 (&acc)[2][2][4][2], const pg8::Unit& u, int wr, int wc, int fr, int fq) const {
;     ...
;         if (cat == 0 || cat == 3 || cat == 4 || cat == 6 || cat == 7) {
;             bf16_t* base; int pitch;
;             if (cat == 0) { base = (bf16_t*)(ws + WS_QB); pitch = 512; } else if (cat == 3) { base = (bf16_t*)(ws + WS_YC); pitch = 1024; }
;             else if (cat == 4) { base = (bf16_t*)(ws + WS_QE); pitch = 512; } else if (cat == 6) { base = (bf16_t*)(ws + WS_VTH); pitch = 512; } else { base = (bf16_t*)(ws + WS_YC) + 512; pitch = 1024; }
; #pragma unroll
;             for (int ai = 0; ai < 2; ++ai)
; #pragma unroll
;                 for (int m = 0; m < 4; ++m) { const int r = rowb + ai * 128 + m * 16; const float sc = rs[ai][m];
; #pragma unroll
;                     for (int bj = 0; bj < 2; ++bj) { u32x4 w;
; #pragma unroll
;                         for (int n = 0; n < 2; ++n) { f32x4 v = acc[ai][bj][m][n] * sc;
;                             if (cat == 0) v = v * QSCALE; else if (cat != 6) { v[0] = fsilu(v[0]); v[1] = fsilu(v[1]); v[2] = fsilu(v[2]); v[3] = fsilu(v[3]); }
;                             w[2 * n] = pk2(v[0], v[1]); w[2 * n + 1] = pk2(v[2], v[3]); }
;                         *(u32x4*)(base + (size_t)r * pitch + cb + bj * 128) = w; } }
.Lbf16_q:
	s_cmp_lg_u32 s47, 6
	s_cselect_b64 s[6:7], -1, 0
	s_waitcnt lgkmcnt(0)
	v_pk_mul_f32 v[162:163], v[158:159], v[200:201] op_sel_hi:[1,0]
	v_cndmask_b32_e64 v158, 0, 1, s[6:7]
	v_pk_mul_f32 v[164:165], v[160:161], v[200:201] op_sel_hi:[1,0]
	v_cmp_ne_u32_e64 s[44:45], 1, v158
	s_movk_i32 s57, 0x4000
	v_pk_mul_f32 v[160:161], v[164:165], s[4:5] op_sel_hi:[1,0]
	v_pk_mul_f32 v[158:159], v[162:163], s[4:5] op_sel_hi:[1,0]
	v_mov_b32_e32 v166, v200
	v_mov_b32_e32 v167, v200
	v_mov_b32_e32 v162, v200
	v_mov_b32_e32 v163, v200
	v_pk_mul_f32 v[156:157], v[156:157], v[162:163]
	v_pk_mul_f32 v[154:155], v[154:155], v[166:167]
	v_pk_mul_f32 v[164:165], v[156:157], s[4:5] op_sel_hi:[1,0]
	v_pk_mul_f32 v[162:163], v[154:155], s[4:5] op_sel_hi:[1,0]
	s_add_u32 s6, s22, s60
	s_addc_u32 s7, s23, s61
	v_ashrrev_i32_e32 v203, 31, v202
	v_cvt_pk_bf16_f32 v154, v158, v159
	v_lshl_add_u64 v[158:159], v[202:203], 1, s[6:7]
	v_mad_i64_i32 v[156:157], s[6:7], s56, v192, 0
	v_cvt_pk_bf16_f32 v155, v160, v161
	v_lshl_add_u64 v[160:161], v[156:157], 1, v[158:159]
	v_cvt_pk_bf16_f32 v156, v162, v163
	v_cvt_pk_bf16_f32 v157, v164, v165
	global_store_dwordx4 v[160:161], v[154:157], off
	s_nop 1
	v_mov_b32_e32 v154, v200
	v_mov_b32_e32 v155, v200
	v_pk_mul_f32 v[156:157], v[152:153], v[154:155]
	v_pk_mul_f32 v[154:155], v[150:151], v[166:167]
	v_pk_mul_f32 v[152:153], v[156:157], s[4:5] op_sel_hi:[1,0]
	v_pk_mul_f32 v[150:151], v[154:155], s[4:5] op_sel_hi:[1,0]
	v_mov_b32_e32 v154, v200
	v_mov_b32_e32 v155, v200
	v_pk_mul_f32 v[148:149], v[148:149], v[154:155]
	v_pk_mul_f32 v[146:147], v[146:147], v[166:167]
	v_pk_mul_f32 v[156:157], v[148:149], s[4:5] op_sel_hi:[1,0]
	v_pk_mul_f32 v[154:155], v[146:147], s[4:5] op_sel_hi:[1,0]
	v_cvt_pk_bf16_f32 v146, v150, v151
	v_cvt_pk_bf16_f32 v147, v152, v153
	v_cvt_pk_bf16_f32 v148, v154, v155
	v_cvt_pk_bf16_f32 v149, v156, v157
	global_store_dwordx4 v[160:161], v[146:149], off offset:256
	s_nop 1
	v_pk_mul_f32 v[146:147], v[142:143], v[200:201] op_sel:[0,1]
	v_pk_mul_f32 v[148:149], v[144:145], v[200:201] op_sel:[0,1]
	v_pk_mul_f32 v[144:145], v[148:149], s[4:5] op_sel_hi:[1,0]
	v_pk_mul_f32 v[142:143], v[146:147], s[4:5] op_sel_hi:[1,0]
	v_mov_b32_e32 v200, v201
	v_mov_b32_e32 v146, v201
	v_mov_b32_e32 v147, v201
	v_pk_mul_f32 v[140:141], v[140:141], v[146:147]
	v_pk_mul_f32 v[138:139], v[138:139], v[200:201]
	v_pk_mul_f32 v[148:149], v[140:141], s[4:5] op_sel_hi:[1,0]
	v_pk_mul_f32 v[146:147], v[138:139], s[4:5] op_sel_hi:[1,0]
	v_add_u32_e32 v140, 16, v192
	v_mad_i64_i32 v[140:141], s[6:7], s56, v140, 0
	v_cvt_pk_bf16_f32 v138, v142, v143
	v_cvt_pk_bf16_f32 v139, v144, v145
	v_lshl_add_u64 v[142:143], v[140:141], 1, v[158:159]
	v_cvt_pk_bf16_f32 v140, v146, v147
	v_cvt_pk_bf16_f32 v141, v148, v149
	global_store_dwordx4 v[142:143], v[138:141], off
	s_nop 1
	v_mov_b32_e32 v138, v201
	v_mov_b32_e32 v139, v201
	v_pk_mul_f32 v[140:141], v[136:137], v[138:139]
	v_pk_mul_f32 v[138:139], v[134:135], v[200:201]
	v_pk_mul_f32 v[136:137], v[140:141], s[4:5] op_sel_hi:[1,0]
	v_pk_mul_f32 v[134:135], v[138:139], s[4:5] op_sel_hi:[1,0]
	v_mov_b32_e32 v138, v201
	v_mov_b32_e32 v139, v201
	v_pk_mul_f32 v[132:133], v[132:133], v[138:139]
	v_pk_mul_f32 v[130:131], v[130:131], v[200:201]
	v_pk_mul_f32 v[140:141], v[132:133], s[4:5] op_sel_hi:[1,0]
	v_pk_mul_f32 v[138:139], v[130:131], s[4:5] op_sel_hi:[1,0]
	v_cvt_pk_bf16_f32 v130, v134, v135
	v_cvt_pk_bf16_f32 v131, v136, v137
	v_cvt_pk_bf16_f32 v132, v138, v139
	v_cvt_pk_bf16_f32 v133, v140, v141
	global_store_dwordx4 v[142:143], v[130:133], off offset:256
	s_nop 1
	v_pk_mul_f32 v[130:131], v[126:127], v[198:199] op_sel_hi:[1,0]
	v_pk_mul_f32 v[132:133], v[128:129], v[198:199] op_sel_hi:[1,0]
	v_pk_mul_f32 v[128:129], v[132:133], s[4:5] op_sel_hi:[1,0]
	v_pk_mul_f32 v[126:127], v[130:131], s[4:5] op_sel_hi:[1,0]
	v_mov_b32_e32 v134, v198
	v_mov_b32_e32 v135, v198
	v_mov_b32_e32 v130, v198
	v_mov_b32_e32 v131, v198
	v_pk_mul_f32 v[124:125], v[124:125], v[130:131]
	v_pk_mul_f32 v[122:123], v[122:123], v[134:135]
	v_pk_mul_f32 v[132:133], v[124:125], s[4:5] op_sel_hi:[1,0]
	v_pk_mul_f32 v[130:131], v[122:123], s[4:5] op_sel_hi:[1,0]
	v_add_u32_e32 v124, 32, v192
	v_mad_i64_i32 v[124:125], s[6:7], s56, v124, 0
	v_cvt_pk_bf16_f32 v122, v126, v127
	v_cvt_pk_bf16_f32 v123, v128, v129
	v_lshl_add_u64 v[126:127], v[124:125], 1, v[158:159]
	v_cvt_pk_bf16_f32 v124, v130, v131
	v_cvt_pk_bf16_f32 v125, v132, v133
	global_store_dwordx4 v[126:127], v[122:125], off
	s_nop 1
	v_mov_b32_e32 v122, v198
	v_mov_b32_e32 v123, v198
	v_pk_mul_f32 v[124:125], v[120:121], v[122:123]
	v_pk_mul_f32 v[122:123], v[118:119], v[134:135]
	v_pk_mul_f32 v[120:121], v[124:125], s[4:5] op_sel_hi:[1,0]
	v_pk_mul_f32 v[118:119], v[122:123], s[4:5] op_sel_hi:[1,0]
	v_mov_b32_e32 v122, v198
	v_mov_b32_e32 v123, v198
	v_pk_mul_f32 v[116:117], v[116:117], v[122:123]
	v_pk_mul_f32 v[114:115], v[114:115], v[134:135]
	v_pk_mul_f32 v[124:125], v[116:117], s[4:5] op_sel_hi:[1,0]
	v_pk_mul_f32 v[122:123], v[114:115], s[4:5] op_sel_hi:[1,0]
	v_cvt_pk_bf16_f32 v114, v118, v119
	v_cvt_pk_bf16_f32 v115, v120, v121
	v_cvt_pk_bf16_f32 v116, v122, v123
	v_cvt_pk_bf16_f32 v117, v124, v125
	global_store_dwordx4 v[126:127], v[114:117], off offset:256
	s_nop 1
	v_pk_mul_f32 v[114:115], v[106:107], v[198:199] op_sel:[0,1]
	v_pk_mul_f32 v[116:117], v[108:109], v[198:199] op_sel:[0,1]
	v_pk_mul_f32 v[108:109], v[116:117], s[4:5] op_sel_hi:[1,0]
	v_pk_mul_f32 v[106:107], v[114:115], s[4:5] op_sel_hi:[1,0]
	v_mov_b32_e32 v198, v199
	v_mov_b32_e32 v114, v199
	v_mov_b32_e32 v115, v199
	v_pk_mul_f32 v[88:89], v[88:89], v[114:115]
; __device__ __forceinline__ float fsilu(float x) { return x * __builtin_amdgcn_rcpf(1.f + __expf(-x)); }
;     __device__ __forceinline__ void operator()(const f32x4 (&acc)[2][2][4][2], const pg8::Unit& u, int wr, int wc, int fr, int fq) const {
;     ...
;                 for (int m = 0; m < 4; ++m) { const int r = rowb + ai * 128 + m * 16; const float sc = rs[ai][m];
; #pragma unroll
;                     for (int bj = 0; bj < 2; ++bj) { u32x4 w;
; #pragma unroll
;                         for (int n = 0; n < 2; ++n) { f32x4 v = acc[ai][bj][m][n] * sc;
;                             if (cat == 0) v = v * QSCALE; else if (cat != 6) { v[0] = fsilu(v[0]); v[1] = fsilu(v[1]); v[2] = fsilu(v[2]); v[3] = fsilu(v[3]); }
;                             w[2 * n] = pk2(v[0], v[1]); w[2 * n + 1] = pk2(v[2], v[3]); }
;                         *(u32x4*)(base + (size_t)r * pitch + cb + bj * 128) = w; } }
	v_pk_mul_f32 v[86:87], v[86:87], v[198:199]
	v_pk_mul_f32 v[116:117], v[88:89], s[4:5] op_sel_hi:[1,0]
	v_pk_mul_f32 v[114:115], v[86:87], s[4:5] op_sel_hi:[1,0]
	v_add_u32_e32 v88, 48, v192
	v_mad_i64_i32 v[88:89], s[6:7], s56, v88, 0
	v_cvt_pk_bf16_f32 v86, v106, v107
	v_cvt_pk_bf16_f32 v87, v108, v109
	v_lshl_add_u64 v[106:107], v[88:89], 1, v[158:159]
	v_cvt_pk_bf16_f32 v88, v114, v115
	v_cvt_pk_bf16_f32 v89, v116, v117
	global_store_dwordx4 v[106:107], v[86:89], off
	s_nop 1
	v_mov_b32_e32 v86, v199
	v_mov_b32_e32 v87, v199
	v_pk_mul_f32 v[88:89], v[72:73], v[86:87]
	v_pk_mul_f32 v[86:87], v[70:71], v[198:199]
	v_pk_mul_f32 v[72:73], v[88:89], s[4:5] op_sel_hi:[1,0]
	v_pk_mul_f32 v[70:71], v[86:87], s[4:5] op_sel_hi:[1,0]
	v_mov_b32_e32 v86, v199
	v_mov_b32_e32 v87, v199
	v_pk_mul_f32 v[68:69], v[68:69], v[86:87]
	v_pk_mul_f32 v[66:67], v[66:67], v[198:199]
	v_pk_mul_f32 v[88:89], v[68:69], s[4:5] op_sel_hi:[1,0]
	v_pk_mul_f32 v[86:87], v[66:67], s[4:5] op_sel_hi:[1,0]
	v_cvt_pk_bf16_f32 v66, v70, v71
	v_cvt_pk_bf16_f32 v67, v72, v73
	v_cvt_pk_bf16_f32 v68, v86, v87
	v_cvt_pk_bf16_f32 v69, v88, v89
	global_store_dwordx4 v[106:107], v[66:69], off offset:256
	s_nop 1
	v_pk_mul_f32 v[66:67], v[62:63], v[196:197] op_sel_hi:[1,0]
	v_pk_mul_f32 v[68:69], v[64:65], v[196:197] op_sel_hi:[1,0]
	v_pk_mul_f32 v[64:65], v[68:69], s[4:5] op_sel_hi:[1,0]
	v_pk_mul_f32 v[62:63], v[66:67], s[4:5] op_sel_hi:[1,0]
	v_mov_b32_e32 v70, v196
	v_mov_b32_e32 v71, v196
	v_mov_b32_e32 v66, v196
	v_mov_b32_e32 v67, v196
	v_pk_mul_f32 v[60:61], v[60:61], v[66:67]
	v_pk_mul_f32 v[58:59], v[58:59], v[70:71]
	v_pk_mul_f32 v[68:69], v[60:61], s[4:5] op_sel_hi:[1,0]
	v_pk_mul_f32 v[66:67], v[58:59], s[4:5] op_sel_hi:[1,0]
	v_add_u32_e32 v60, 0x80, v192
	v_mad_i64_i32 v[60:61], s[6:7], s56, v60, 0
	v_cvt_pk_bf16_f32 v58, v62, v63
	v_cvt_pk_bf16_f32 v59, v64, v65
	v_lshl_add_u64 v[62:63], v[60:61], 1, v[158:159]
	v_cvt_pk_bf16_f32 v60, v66, v67
	v_cvt_pk_bf16_f32 v61, v68, v69
	global_store_dwordx4 v[62:63], v[58:61], off
	s_nop 1
	v_mov_b32_e32 v58, v196
	v_mov_b32_e32 v59, v196
	v_pk_mul_f32 v[60:61], v[56:57], v[58:59]
	v_pk_mul_f32 v[58:59], v[54:55], v[70:71]
	v_pk_mul_f32 v[56:57], v[60:61], s[4:5] op_sel_hi:[1,0]
	v_pk_mul_f32 v[54:55], v[58:59], s[4:5] op_sel_hi:[1,0]
	v_mov_b32_e32 v58, v196
	v_mov_b32_e32 v59, v196
	v_pk_mul_f32 v[52:53], v[52:53], v[58:59]
	v_pk_mul_f32 v[50:51], v[50:51], v[70:71]
	v_pk_mul_f32 v[60:61], v[52:53], s[4:5] op_sel_hi:[1,0]
	v_pk_mul_f32 v[58:59], v[50:51], s[4:5] op_sel_hi:[1,0]
	v_cvt_pk_bf16_f32 v50, v54, v55
	v_cvt_pk_bf16_f32 v51, v56, v57
	v_cvt_pk_bf16_f32 v52, v58, v59
	v_cvt_pk_bf16_f32 v53, v60, v61
	global_store_dwordx4 v[62:63], v[50:53], off offset:256
	s_nop 1
	v_pk_mul_f32 v[50:51], v[46:47], v[196:197] op_sel:[0,1]
	v_pk_mul_f32 v[52:53], v[48:49], v[196:197] op_sel:[0,1]
	v_pk_mul_f32 v[48:49], v[52:53], s[4:5] op_sel_hi:[1,0]
	v_pk_mul_f32 v[46:47], v[50:51], s[4:5] op_sel_hi:[1,0]
	v_mov_b32_e32 v196, v197
	v_mov_b32_e32 v50, v197
	v_mov_b32_e32 v51, v197
	v_pk_mul_f32 v[44:45], v[44:45], v[50:51]
	v_pk_mul_f32 v[42:43], v[42:43], v[196:197]
	v_pk_mul_f32 v[52:53], v[44:45], s[4:5] op_sel_hi:[1,0]
	v_pk_mul_f32 v[50:51], v[42:43], s[4:5] op_sel_hi:[1,0]
	v_add_u32_e32 v44, 0x90, v192
	v_mad_i64_i32 v[44:45], s[6:7], s56, v44, 0
	v_cvt_pk_bf16_f32 v42, v46, v47
	v_cvt_pk_bf16_f32 v43, v48, v49
	v_lshl_add_u64 v[46:47], v[44:45], 1, v[158:159]
	v_cvt_pk_bf16_f32 v44, v50, v51
	v_cvt_pk_bf16_f32 v45, v52, v53
	global_store_dwordx4 v[46:47], v[42:45], off
	s_nop 1
	v_mov_b32_e32 v42, v197
	v_mov_b32_e32 v43, v197
	v_pk_mul_f32 v[44:45], v[40:41], v[42:43]
	v_pk_mul_f32 v[42:43], v[38:39], v[196:197]
	v_pk_mul_f32 v[40:41], v[44:45], s[4:5] op_sel_hi:[1,0]
	v_pk_mul_f32 v[38:39], v[42:43], s[4:5] op_sel_hi:[1,0]
	v_mov_b32_e32 v42, v197
	v_mov_b32_e32 v43, v197
	v_pk_mul_f32 v[36:37], v[36:37], v[42:43]
	v_pk_mul_f32 v[34:35], v[34:35], v[196:197]
	v_pk_mul_f32 v[44:45], v[36:37], s[4:5] op_sel_hi:[1,0]
	v_pk_mul_f32 v[42:43], v[34:35], s[4:5] op_sel_hi:[1,0]
	v_cvt_pk_bf16_f32 v34, v38, v39
	v_cvt_pk_bf16_f32 v35, v40, v41
	v_cvt_pk_bf16_f32 v36, v42, v43
	v_cvt_pk_bf16_f32 v37, v44, v45
	global_store_dwordx4 v[46:47], v[34:37], off offset:256
	s_nop 1
	v_pk_mul_f32 v[34:35], v[30:31], v[194:195] op_sel_hi:[1,0]
	v_pk_mul_f32 v[36:37], v[32:33], v[194:195] op_sel_hi:[1,0]
	v_pk_mul_f32 v[32:33], v[36:37], s[4:5] op_sel_hi:[1,0]
	v_pk_mul_f32 v[30:31], v[34:35], s[4:5] op_sel_hi:[1,0]
	v_mov_b32_e32 v38, v194
	v_mov_b32_e32 v39, v194
	v_mov_b32_e32 v34, v194
	v_mov_b32_e32 v35, v194
	v_pk_mul_f32 v[28:29], v[28:29], v[34:35]
	v_pk_mul_f32 v[26:27], v[26:27], v[38:39]
	v_pk_mul_f32 v[36:37], v[28:29], s[4:5] op_sel_hi:[1,0]
	v_pk_mul_f32 v[34:35], v[26:27], s[4:5] op_sel_hi:[1,0]
	v_add_u32_e32 v28, 0xa0, v192
	v_mad_i64_i32 v[28:29], s[6:7], s56, v28, 0
	v_cvt_pk_bf16_f32 v26, v30, v31
	v_cvt_pk_bf16_f32 v27, v32, v33
	v_lshl_add_u64 v[30:31], v[28:29], 1, v[158:159]
	v_cvt_pk_bf16_f32 v28, v34, v35
	v_cvt_pk_bf16_f32 v29, v36, v37
	global_store_dwordx4 v[30:31], v[26:29], off
	s_nop 1
	v_mov_b32_e32 v26, v194
	v_mov_b32_e32 v27, v194
	v_pk_mul_f32 v[28:29], v[24:25], v[26:27]
	v_pk_mul_f32 v[26:27], v[22:23], v[38:39]
	v_pk_mul_f32 v[24:25], v[28:29], s[4:5] op_sel_hi:[1,0]
	v_pk_mul_f32 v[22:23], v[26:27], s[4:5] op_sel_hi:[1,0]
	v_mov_b32_e32 v26, v194
	v_mov_b32_e32 v27, v194
	v_pk_mul_f32 v[20:21], v[20:21], v[26:27]
	v_pk_mul_f32 v[18:19], v[18:19], v[38:39]
	v_pk_mul_f32 v[28:29], v[20:21], s[4:5] op_sel_hi:[1,0]
	v_pk_mul_f32 v[26:27], v[18:19], s[4:5] op_sel_hi:[1,0]
	v_cvt_pk_bf16_f32 v18, v22, v23
; __device__ __forceinline__ float fsilu(float x) { return x * __builtin_amdgcn_rcpf(1.f + __expf(-x)); }
;     __device__ __forceinline__ void operator()(const f32x4 (&acc)[2][2][4][2], const pg8::Unit& u, int wr, int wc, int fr, int fq) const {
;     ...
;             if (cat == 0) { base = (bf16_t*)(ws + WS_QB); pitch = 512; } else if (cat == 3) { base = (bf16_t*)(ws + WS_YC); pitch = 1024; }
;             else if (cat == 4) { base = (bf16_t*)(ws + WS_QE); pitch = 512; } else if (cat == 6) { base = (bf16_t*)(ws + WS_VTH); pitch = 512; } else { base = (bf16_t*)(ws + WS_YC) + 512; pitch = 1024; }
; #pragma unroll
;             for (int ai = 0; ai < 2; ++ai)
; #pragma unroll
;                 for (int m = 0; m < 4; ++m) { const int r = rowb + ai * 128 + m * 16; const float sc = rs[ai][m];
; #pragma unroll
;                     for (int bj = 0; bj < 2; ++bj) { u32x4 w;
; #pragma unroll
;                         for (int n = 0; n < 2; ++n) { f32x4 v = acc[ai][bj][m][n] * sc;
;                             if (cat == 0) v = v * QSCALE; else if (cat != 6) { v[0] = fsilu(v[0]); v[1] = fsilu(v[1]); v[2] = fsilu(v[2]); v[3] = fsilu(v[3]); }
;                             w[2 * n] = pk2(v[0], v[1]); w[2 * n + 1] = pk2(v[2], v[3]); }
;                         *(u32x4*)(base + (size_t)r * pitch + cb + bj * 128) = w; } }
	v_cvt_pk_bf16_f32 v19, v24, v25
	v_cvt_pk_bf16_f32 v20, v26, v27
	v_cvt_pk_bf16_f32 v21, v28, v29
	global_store_dwordx4 v[30:31], v[18:21], off offset:256
	s_nop 1
	v_pk_mul_f32 v[18:19], v[14:15], v[194:195] op_sel:[0,1]
	v_pk_mul_f32 v[20:21], v[16:17], v[194:195] op_sel:[0,1]
	v_pk_mul_f32 v[16:17], v[20:21], s[4:5] op_sel_hi:[1,0]
	v_pk_mul_f32 v[14:15], v[18:19], s[4:5] op_sel_hi:[1,0]
	v_mov_b32_e32 v194, v195
	v_mov_b32_e32 v18, v195
	v_mov_b32_e32 v19, v195
	v_pk_mul_f32 v[12:13], v[12:13], v[18:19]
	v_pk_mul_f32 v[10:11], v[10:11], v[194:195]
	v_pk_mul_f32 v[20:21], v[12:13], s[4:5] op_sel_hi:[1,0]
	v_pk_mul_f32 v[18:19], v[10:11], s[4:5] op_sel_hi:[1,0]
	v_add_u32_e32 v12, 0xb0, v192
	v_mad_i64_i32 v[12:13], s[6:7], s56, v12, 0
	v_cvt_pk_bf16_f32 v10, v14, v15
	v_cvt_pk_bf16_f32 v11, v16, v17
	v_lshl_add_u64 v[14:15], v[12:13], 1, v[158:159]
	v_cvt_pk_bf16_f32 v12, v18, v19
	v_cvt_pk_bf16_f32 v13, v20, v21
	global_store_dwordx4 v[14:15], v[10:13], off
	s_nop 1
	v_mov_b32_e32 v10, v195
	v_mov_b32_e32 v11, v195
	v_pk_mul_f32 v[12:13], v[8:9], v[10:11]
	v_pk_mul_f32 v[10:11], v[6:7], v[194:195]
	v_pk_mul_f32 v[8:9], v[12:13], s[4:5] op_sel_hi:[1,0]
	v_pk_mul_f32 v[6:7], v[10:11], s[4:5] op_sel_hi:[1,0]
	v_mov_b32_e32 v10, v195
	v_mov_b32_e32 v11, v195
	v_pk_mul_f32 v[4:5], v[4:5], v[10:11]
	v_pk_mul_f32 v[2:3], v[2:3], v[194:195]
	v_pk_mul_f32 v[12:13], v[4:5], s[4:5] op_sel_hi:[1,0]
	v_pk_mul_f32 v[10:11], v[2:3], s[4:5] op_sel_hi:[1,0]
	v_cvt_pk_bf16_f32 v2, v6, v7
	v_cvt_pk_bf16_f32 v3, v8, v9
	v_cvt_pk_bf16_f32 v4, v10, v11
	v_cvt_pk_bf16_f32 v5, v12, v13
	global_store_dwordx4 v[14:15], v[2:5], off offset:256
	s_nop 1
	s_branch .Lbf16_join
.Lbf16_plain:
	s_cmp_lg_u32 s47, 6
	s_cselect_b64 s[6:7], -1, 0
	s_waitcnt lgkmcnt(0)
	v_pk_mul_f32 v[162:163], v[158:159], v[200:201] op_sel_hi:[1,0]
	v_cndmask_b32_e64 v158, 0, 1, s[6:7]
	v_pk_mul_f32 v[164:165], v[160:161], v[200:201] op_sel_hi:[1,0]
	v_cmp_ne_u32_e64 s[44:45], 1, v158
	s_movk_i32 s57, 0x4000
	v_mov_b64_e32 v[158:159], v[162:163]
	v_mov_b64_e32 v[160:161], v[164:165]
	v_mov_b32_e32 v166, v200
	v_mov_b32_e32 v167, v200
	v_mov_b32_e32 v162, v200
	v_mov_b32_e32 v163, v200
	v_pk_mul_f32 v[156:157], v[156:157], v[162:163]
	v_pk_mul_f32 v[154:155], v[154:155], v[166:167]
	v_mov_b64_e32 v[164:165], v[156:157]
	v_mov_b64_e32 v[162:163], v[154:155]
	s_add_u32 s6, s22, s60
	s_addc_u32 s7, s23, s61
	v_ashrrev_i32_e32 v203, 31, v202
	v_cvt_pk_bf16_f32 v154, v158, v159
	v_lshl_add_u64 v[158:159], v[202:203], 1, s[6:7]
	v_mad_i64_i32 v[156:157], s[6:7], s56, v192, 0
	v_cvt_pk_bf16_f32 v155, v160, v161
	v_lshl_add_u64 v[160:161], v[156:157], 1, v[158:159]
	v_cvt_pk_bf16_f32 v156, v162, v163
	v_cvt_pk_bf16_f32 v157, v164, v165
	global_store_dwordx4 v[160:161], v[154:157], off
	s_nop 1
	v_mov_b32_e32 v154, v200
	v_mov_b32_e32 v155, v200
	v_pk_mul_f32 v[156:157], v[152:153], v[154:155]
	v_pk_mul_f32 v[154:155], v[150:151], v[166:167]
	v_mov_b64_e32 v[150:151], v[154:155]
	v_mov_b64_e32 v[152:153], v[156:157]
	v_mov_b32_e32 v154, v200
	v_mov_b32_e32 v155, v200
	v_pk_mul_f32 v[148:149], v[148:149], v[154:155]
	v_pk_mul_f32 v[146:147], v[146:147], v[166:167]
	v_mov_b64_e32 v[156:157], v[148:149]
	v_mov_b64_e32 v[154:155], v[146:147]
	v_cvt_pk_bf16_f32 v146, v150, v151
	v_cvt_pk_bf16_f32 v147, v152, v153
	v_cvt_pk_bf16_f32 v148, v154, v155
	v_cvt_pk_bf16_f32 v149, v156, v157
	global_store_dwordx4 v[160:161], v[146:149], off offset:256
	s_nop 1
	v_pk_mul_f32 v[146:147], v[142:143], v[200:201] op_sel:[0,1]
	v_pk_mul_f32 v[148:149], v[144:145], v[200:201] op_sel:[0,1]
	v_mov_b64_e32 v[142:143], v[146:147]
	v_mov_b64_e32 v[144:145], v[148:149]
	v_mov_b32_e32 v200, v201
	v_mov_b32_e32 v146, v201
	v_mov_b32_e32 v147, v201
	v_pk_mul_f32 v[140:141], v[140:141], v[146:147]
	v_pk_mul_f32 v[138:139], v[138:139], v[200:201]
	v_mov_b64_e32 v[148:149], v[140:141]
	v_mov_b64_e32 v[146:147], v[138:139]
	v_add_u32_e32 v140, 16, v192
	v_mad_i64_i32 v[140:141], s[6:7], s56, v140, 0
	v_cvt_pk_bf16_f32 v138, v142, v143
	v_cvt_pk_bf16_f32 v139, v144, v145
	v_lshl_add_u64 v[142:143], v[140:141], 1, v[158:159]
	v_cvt_pk_bf16_f32 v140, v146, v147
	v_cvt_pk_bf16_f32 v141, v148, v149
	global_store_dwordx4 v[142:143], v[138:141], off
	s_nop 1
	v_mov_b32_e32 v138, v201
	v_mov_b32_e32 v139, v201
	v_pk_mul_f32 v[140:141], v[136:137], v[138:139]
	v_pk_mul_f32 v[138:139], v[134:135], v[200:201]
	v_mov_b64_e32 v[134:135], v[138:139]
	v_mov_b64_e32 v[136:137], v[140:141]
	v_mov_b32_e32 v138, v201
	v_mov_b32_e32 v139, v201
	v_pk_mul_f32 v[132:133], v[132:133], v[138:139]
	v_pk_mul_f32 v[130:131], v[130:131], v[200:201]
	v_mov_b64_e32 v[140:141], v[132:133]
	v_mov_b64_e32 v[138:139], v[130:131]
	v_cvt_pk_bf16_f32 v130, v134, v135
	v_cvt_pk_bf16_f32 v131, v136, v137
	v_cvt_pk_bf16_f32 v132, v138, v139
	v_cvt_pk_bf16_f32 v133, v140, v141
	global_store_dwordx4 v[142:143], v[130:133], off offset:256
	s_nop 1
	v_pk_mul_f32 v[130:131], v[126:127], v[198:199] op_sel_hi:[1,0]
	v_pk_mul_f32 v[132:133], v[128:129], v[198:199] op_sel_hi:[1,0]
	v_mov_b64_e32 v[126:127], v[130:131]
	v_mov_b64_e32 v[128:129], v[132:133]
	v_mov_b32_e32 v134, v198
	v_mov_b32_e32 v135, v198
	v_mov_b32_e32 v130, v198
	v_mov_b32_e32 v131, v198
	v_pk_mul_f32 v[124:125], v[124:125], v[130:131]
	v_pk_mul_f32 v[122:123], v[122:123], v[134:135]
	v_mov_b64_e32 v[132:133], v[124:125]
	v_mov_b64_e32 v[130:131], v[122:123]
	v_add_u32_e32 v124, 32, v192
	v_mad_i64_i32 v[124:125], s[6:7], s56, v124, 0
	v_cvt_pk_bf16_f32 v122, v126, v127
	v_cvt_pk_bf16_f32 v123, v128, v129
	v_lshl_add_u64 v[126:127], v[124:125], 1, v[158:159]
	v_cvt_pk_bf16_f32 v124, v130, v131
; __device__ __forceinline__ float fsilu(float x) { return x * __builtin_amdgcn_rcpf(1.f + __expf(-x)); }
;     __device__ __forceinline__ void operator()(const f32x4 (&acc)[2][2][4][2], const pg8::Unit& u, int wr, int wc, int fr, int fq) const {
;     ...
;                 for (int m = 0; m < 4; ++m) { const int r = rowb + ai * 128 + m * 16; const float sc = rs[ai][m];
; #pragma unroll
;                     for (int bj = 0; bj < 2; ++bj) { u32x4 w;
; #pragma unroll
;                         for (int n = 0; n < 2; ++n) { f32x4 v = acc[ai][bj][m][n] * sc;
;                             if (cat == 0) v = v * QSCALE; else if (cat != 6) { v[0] = fsilu(v[0]); v[1] = fsilu(v[1]); v[2] = fsilu(v[2]); v[3] = fsilu(v[3]); }
;                             w[2 * n] = pk2(v[0], v[1]); w[2 * n + 1] = pk2(v[2], v[3]); }
;                         *(u32x4*)(base + (size_t)r * pitch + cb + bj * 128) = w; } }
	v_cvt_pk_bf16_f32 v125, v132, v133
	global_store_dwordx4 v[126:127], v[122:125], off
	s_nop 1
	v_mov_b32_e32 v122, v198
	v_mov_b32_e32 v123, v198
	v_pk_mul_f32 v[124:125], v[120:121], v[122:123]
	v_pk_mul_f32 v[122:123], v[118:119], v[134:135]
	v_mov_b64_e32 v[118:119], v[122:123]
	v_mov_b64_e32 v[120:121], v[124:125]
	v_mov_b32_e32 v122, v198
	v_mov_b32_e32 v123, v198
	v_pk_mul_f32 v[116:117], v[116:117], v[122:123]
	v_pk_mul_f32 v[114:115], v[114:115], v[134:135]
	v_mov_b64_e32 v[124:125], v[116:117]
	v_mov_b64_e32 v[122:123], v[114:115]
	v_cvt_pk_bf16_f32 v114, v118, v119
	v_cvt_pk_bf16_f32 v115, v120, v121
	v_cvt_pk_bf16_f32 v116, v122, v123
	v_cvt_pk_bf16_f32 v117, v124, v125
	global_store_dwordx4 v[126:127], v[114:117], off offset:256
	s_nop 1
	v_pk_mul_f32 v[114:115], v[106:107], v[198:199] op_sel:[0,1]
	v_pk_mul_f32 v[116:117], v[108:109], v[198:199] op_sel:[0,1]
	v_mov_b64_e32 v[106:107], v[114:115]
	v_mov_b64_e32 v[108:109], v[116:117]
	v_mov_b32_e32 v198, v199
	v_mov_b32_e32 v114, v199
	v_mov_b32_e32 v115, v199
	v_pk_mul_f32 v[88:89], v[88:89], v[114:115]
	v_pk_mul_f32 v[86:87], v[86:87], v[198:199]
	v_mov_b64_e32 v[116:117], v[88:89]
	v_mov_b64_e32 v[114:115], v[86:87]
	v_add_u32_e32 v88, 48, v192
	v_mad_i64_i32 v[88:89], s[6:7], s56, v88, 0
	v_cvt_pk_bf16_f32 v86, v106, v107
	v_cvt_pk_bf16_f32 v87, v108, v109
	v_lshl_add_u64 v[106:107], v[88:89], 1, v[158:159]
	v_cvt_pk_bf16_f32 v88, v114, v115
	v_cvt_pk_bf16_f32 v89, v116, v117
	global_store_dwordx4 v[106:107], v[86:89], off
	s_nop 1
	v_mov_b32_e32 v86, v199
	v_mov_b32_e32 v87, v199
	v_pk_mul_f32 v[88:89], v[72:73], v[86:87]
	v_pk_mul_f32 v[86:87], v[70:71], v[198:199]
	v_mov_b64_e32 v[70:71], v[86:87]
	v_mov_b64_e32 v[72:73], v[88:89]
	v_mov_b32_e32 v86, v199
	v_mov_b32_e32 v87, v199
	v_pk_mul_f32 v[68:69], v[68:69], v[86:87]
	v_pk_mul_f32 v[66:67], v[66:67], v[198:199]
	v_mov_b64_e32 v[88:89], v[68:69]
	v_mov_b64_e32 v[86:87], v[66:67]
	v_cvt_pk_bf16_f32 v66, v70, v71
	v_cvt_pk_bf16_f32 v67, v72, v73
	v_cvt_pk_bf16_f32 v68, v86, v87
	v_cvt_pk_bf16_f32 v69, v88, v89
	global_store_dwordx4 v[106:107], v[66:69], off offset:256
	s_nop 1
	v_pk_mul_f32 v[66:67], v[62:63], v[196:197] op_sel_hi:[1,0]
	v_pk_mul_f32 v[68:69], v[64:65], v[196:197] op_sel_hi:[1,0]
	v_mov_b64_e32 v[62:63], v[66:67]
	v_mov_b64_e32 v[64:65], v[68:69]
	v_mov_b32_e32 v70, v196
	v_mov_b32_e32 v71, v196
	v_mov_b32_e32 v66, v196
	v_mov_b32_e32 v67, v196
	v_pk_mul_f32 v[60:61], v[60:61], v[66:67]
	v_pk_mul_f32 v[58:59], v[58:59], v[70:71]
	v_mov_b64_e32 v[68:69], v[60:61]
	v_mov_b64_e32 v[66:67], v[58:59]
	v_add_u32_e32 v60, 0x80, v192
	v_mad_i64_i32 v[60:61], s[6:7], s56, v60, 0
	v_cvt_pk_bf16_f32 v58, v62, v63
	v_cvt_pk_bf16_f32 v59, v64, v65
	v_lshl_add_u64 v[62:63], v[60:61], 1, v[158:159]
	v_cvt_pk_bf16_f32 v60, v66, v67
	v_cvt_pk_bf16_f32 v61, v68, v69
	global_store_dwordx4 v[62:63], v[58:61], off
	s_nop 1
	v_mov_b32_e32 v58, v196
	v_mov_b32_e32 v59, v196
	v_pk_mul_f32 v[60:61], v[56:57], v[58:59]
	v_pk_mul_f32 v[58:59], v[54:55], v[70:71]
	v_mov_b64_e32 v[54:55], v[58:59]
	v_mov_b64_e32 v[56:57], v[60:61]
	v_mov_b32_e32 v58, v196
	v_mov_b32_e32 v59, v196
	v_pk_mul_f32 v[52:53], v[52:53], v[58:59]
	v_pk_mul_f32 v[50:51], v[50:51], v[70:71]
	v_mov_b64_e32 v[60:61], v[52:53]
	v_mov_b64_e32 v[58:59], v[50:51]
	v_cvt_pk_bf16_f32 v50, v54, v55
	v_cvt_pk_bf16_f32 v51, v56, v57
	v_cvt_pk_bf16_f32 v52, v58, v59
	v_cvt_pk_bf16_f32 v53, v60, v61
	global_store_dwordx4 v[62:63], v[50:53], off offset:256
	s_nop 1
	v_pk_mul_f32 v[50:51], v[46:47], v[196:197] op_sel:[0,1]
	v_pk_mul_f32 v[52:53], v[48:49], v[196:197] op_sel:[0,1]
	v_mov_b64_e32 v[46:47], v[50:51]
	v_mov_b64_e32 v[48:49], v[52:53]
	v_mov_b32_e32 v196, v197
	v_mov_b32_e32 v50, v197
	v_mov_b32_e32 v51, v197
	v_pk_mul_f32 v[44:45], v[44:45], v[50:51]
; __device__ __forceinline__ float fsilu(float x) { return x * __builtin_amdgcn_rcpf(1.f + __expf(-x)); }
;     __device__ __forceinline__ void operator()(const f32x4 (&acc)[2][2][4][2], const pg8::Unit& u, int wr, int wc, int fr, int fq) const {
;     ...
;                 for (int m = 0; m < 4; ++m) { const int r = rowb + ai * 128 + m * 16; const float sc = rs[ai][m];
; #pragma unroll
;                     for (int bj = 0; bj < 2; ++bj) { u32x4 w;
; #pragma unroll
;                         for (int n = 0; n < 2; ++n) { f32x4 v = acc[ai][bj][m][n] * sc;
;                             if (cat == 0) v = v * QSCALE; else if (cat != 6) { v[0] = fsilu(v[0]); v[1] = fsilu(v[1]); v[2] = fsilu(v[2]); v[3] = fsilu(v[3]); }
;                             w[2 * n] = pk2(v[0], v[1]); w[2 * n + 1] = pk2(v[2], v[3]); }
;                         *(u32x4*)(base + (size_t)r * pitch + cb + bj * 128) = w; } }
	v_pk_mul_f32 v[42:43], v[42:43], v[196:197]
	v_mov_b64_e32 v[52:53], v[44:45]
	v_mov_b64_e32 v[50:51], v[42:43]
	v_add_u32_e32 v44, 0x90, v192
	v_mad_i64_i32 v[44:45], s[6:7], s56, v44, 0
	v_cvt_pk_bf16_f32 v42, v46, v47
	v_cvt_pk_bf16_f32 v43, v48, v49
	v_lshl_add_u64 v[46:47], v[44:45], 1, v[158:159]
	v_cvt_pk_bf16_f32 v44, v50, v51
	v_cvt_pk_bf16_f32 v45, v52, v53
	global_store_dwordx4 v[46:47], v[42:45], off
	s_nop 1
	v_mov_b32_e32 v42, v197
	v_mov_b32_e32 v43, v197
	v_pk_mul_f32 v[44:45], v[40:41], v[42:43]
	v_pk_mul_f32 v[42:43], v[38:39], v[196:197]
	v_mov_b64_e32 v[38:39], v[42:43]
	v_mov_b64_e32 v[40:41], v[44:45]
	v_mov_b32_e32 v42, v197
	v_mov_b32_e32 v43, v197
	v_pk_mul_f32 v[36:37], v[36:37], v[42:43]
	v_pk_mul_f32 v[34:35], v[34:35], v[196:197]
	v_mov_b64_e32 v[44:45], v[36:37]
	v_mov_b64_e32 v[42:43], v[34:35]
	v_cvt_pk_bf16_f32 v34, v38, v39
	v_cvt_pk_bf16_f32 v35, v40, v41
	v_cvt_pk_bf16_f32 v36, v42, v43
	v_cvt_pk_bf16_f32 v37, v44, v45
	global_store_dwordx4 v[46:47], v[34:37], off offset:256
	s_nop 1
	v_pk_mul_f32 v[34:35], v[30:31], v[194:195] op_sel_hi:[1,0]
	v_pk_mul_f32 v[36:37], v[32:33], v[194:195] op_sel_hi:[1,0]
	v_mov_b64_e32 v[30:31], v[34:35]
	v_mov_b64_e32 v[32:33], v[36:37]
	v_mov_b32_e32 v38, v194
	v_mov_b32_e32 v39, v194
	v_mov_b32_e32 v34, v194
	v_mov_b32_e32 v35, v194
	v_pk_mul_f32 v[28:29], v[28:29], v[34:35]
	v_pk_mul_f32 v[26:27], v[26:27], v[38:39]
	v_mov_b64_e32 v[36:37], v[28:29]
	v_mov_b64_e32 v[34:35], v[26:27]
	v_add_u32_e32 v28, 0xa0, v192
	v_mad_i64_i32 v[28:29], s[6:7], s56, v28, 0
	v_cvt_pk_bf16_f32 v26, v30, v31
	v_cvt_pk_bf16_f32 v27, v32, v33
	v_lshl_add_u64 v[30:31], v[28:29], 1, v[158:159]
	v_cvt_pk_bf16_f32 v28, v34, v35
	v_cvt_pk_bf16_f32 v29, v36, v37
	global_store_dwordx4 v[30:31], v[26:29], off
	s_nop 1
	v_mov_b32_e32 v26, v194
	v_mov_b32_e32 v27, v194
	v_pk_mul_f32 v[28:29], v[24:25], v[26:27]
	v_pk_mul_f32 v[26:27], v[22:23], v[38:39]
	v_mov_b64_e32 v[22:23], v[26:27]
	v_mov_b64_e32 v[24:25], v[28:29]
	v_mov_b32_e32 v26, v194
	v_mov_b32_e32 v27, v194
	v_pk_mul_f32 v[20:21], v[20:21], v[26:27]
	v_pk_mul_f32 v[18:19], v[18:19], v[38:39]
	v_mov_b64_e32 v[28:29], v[20:21]
	v_mov_b64_e32 v[26:27], v[18:19]
	v_cvt_pk_bf16_f32 v18, v22, v23
	v_cvt_pk_bf16_f32 v19, v24, v25
	v_cvt_pk_bf16_f32 v20, v26, v27
	v_cvt_pk_bf16_f32 v21, v28, v29
	global_store_dwordx4 v[30:31], v[18:21], off offset:256
	s_nop 1
	v_pk_mul_f32 v[18:19], v[14:15], v[194:195] op_sel:[0,1]
	v_pk_mul_f32 v[20:21], v[16:17], v[194:195] op_sel:[0,1]
	v_mov_b64_e32 v[14:15], v[18:19]
	v_mov_b64_e32 v[16:17], v[20:21]
	v_mov_b32_e32 v194, v195
	v_mov_b32_e32 v18, v195
	v_mov_b32_e32 v19, v195
	v_pk_mul_f32 v[12:13], v[12:13], v[18:19]
	v_pk_mul_f32 v[10:11], v[10:11], v[194:195]
	v_mov_b64_e32 v[20:21], v[12:13]
	v_mov_b64_e32 v[18:19], v[10:11]
	v_add_u32_e32 v12, 0xb0, v192
	v_mad_i64_i32 v[12:13], s[6:7], s56, v12, 0
	v_cvt_pk_bf16_f32 v10, v14, v15
	v_cvt_pk_bf16_f32 v11, v16, v17
	v_lshl_add_u64 v[14:15], v[12:13], 1, v[158:159]
	v_cvt_pk_bf16_f32 v12, v18, v19
	v_cvt_pk_bf16_f32 v13, v20, v21
	global_store_dwordx4 v[14:15], v[10:13], off
	s_nop 1
	v_mov_b32_e32 v10, v195
	v_mov_b32_e32 v11, v195
	v_pk_mul_f32 v[12:13], v[8:9], v[10:11]
	v_pk_mul_f32 v[10:11], v[6:7], v[194:195]
	v_mov_b64_e32 v[6:7], v[10:11]
	v_mov_b64_e32 v[8:9], v[12:13]
	v_mov_b32_e32 v10, v195
	v_mov_b32_e32 v11, v195
	v_pk_mul_f32 v[4:5], v[4:5], v[10:11]
	v_pk_mul_f32 v[2:3], v[2:3], v[194:195]
	v_mov_b64_e32 v[12:13], v[4:5]
	v_mov_b64_e32 v[10:11], v[2:3]
	v_cvt_pk_bf16_f32 v2, v6, v7
	v_cvt_pk_bf16_f32 v3, v8, v9
	v_cvt_pk_bf16_f32 v4, v10, v11
	v_cvt_pk_bf16_f32 v5, v12, v13
	global_store_dwordx4 v[14:15], v[2:5], off offset:256
	s_nop 1
.Lbf16_join:
	s_and_b64 vcc, exec, s[40:41]
	s_mov_b64 s[22:23], -1
	s_cbranch_vccnz .LBB0_149
	s_waitcnt vmcnt(16)
